# K-loop load segments: M0-hazard s_nop pads removed (the address v_lshl_add_u64 moved between the m0 write and the LDS-DMA load), 58 sites
# speedup vs baseline: 1.0042x; 1.0042x over previous
.Lkprio_5:
.LBB0_57:
	s_add_u32 s22, s0, 0xfffc0080
	s_addc_u32 s23, s1, -1
	s_add_i32 s65, 0, 0x10000
	v_add_u32_e32 v142, s65, v178
	ds_read_b128 v[130:133], v142
	ds_read_b128 v[134:137], v142 offset:1024
	ds_read_b128 v[138:141], v142 offset:2048
	ds_read_b128 v[142:145], v142 offset:3072
	s_cmp_eq_u32 s64, 12
	s_cselect_b32 s49, s37, s23
	s_cselect_b32 s48, s60, s22
	s_cselect_b32 s23, s35, s63
	s_cselect_b32 s22, s61, s62
	v_lshl_add_u64 v[186:187], s[0:1], 0, v[168:169]
	s_add_i32 m0, s47, 0xc000
	ds_read_b128 v[172:175], v180
	ds_read_b128 v[182:185], v180 offset:1024
	ds_read_b128 v[206:209], v180 offset:2048
	ds_read_b128 v[210:213], v180 offset:3072
	ds_read_b128 v[214:217], v180 offset:4096
	ds_read_b128 v[218:221], v180 offset:5120
	ds_read_b128 v[222:225], v180 offset:6144
	ds_read_b128 v[226:229], v180 offset:7168
	global_load_lds_dwordx4 v[186:187], off
	s_add_i32 m0, s47, 0xe000
	v_lshl_add_u64 v[186:187], s[0:1], 0, v[170:171]
	global_load_lds_dwordx4 v[186:187], off
	s_waitcnt lgkmcnt(8)
	s_barrier
	s_waitcnt lgkmcnt(0)
	v_mfma_f32_16x16x32_bf16 v[126:129], v[130:133], v[172:175], v[126:129]
	v_mfma_f32_16x16x32_bf16 v[122:125], v[138:141], v[172:175], v[122:125]
	v_mfma_f32_16x16x32_bf16 v[114:117], v[130:133], v[206:209], v[114:117]
	v_mfma_f32_16x16x32_bf16 v[106:109], v[138:141], v[206:209], v[106:109]
	v_mfma_f32_16x16x32_bf16 v[98:101], v[130:133], v[214:217], v[98:101]
	v_mfma_f32_16x16x32_bf16 v[90:93], v[138:141], v[214:217], v[90:93]
	v_mfma_f32_16x16x32_bf16 v[82:85], v[130:133], v[222:225], v[82:85]
	v_mfma_f32_16x16x32_bf16 v[74:77], v[138:141], v[222:225], v[74:77]
	v_mfma_f32_16x16x32_bf16 v[126:129], v[134:137], v[182:185], v[126:129]
	v_mfma_f32_16x16x32_bf16 v[122:125], v[142:145], v[182:185], v[122:125]
	v_mfma_f32_16x16x32_bf16 v[114:117], v[134:137], v[210:213], v[114:117]
	v_mfma_f32_16x16x32_bf16 v[106:109], v[142:145], v[210:213], v[106:109]
	v_mfma_f32_16x16x32_bf16 v[98:101], v[134:137], v[218:221], v[98:101]
	v_mfma_f32_16x16x32_bf16 v[90:93], v[142:145], v[218:221], v[90:93]
	v_mfma_f32_16x16x32_bf16 v[82:85], v[134:137], v[226:229], v[82:85]
	v_mfma_f32_16x16x32_bf16 v[74:77], v[142:145], v[226:229], v[74:77]
	s_barrier
	s_add_i32 s68, 0, 0x14000
	s_add_i32 s65, s65, s27
	v_add_u32_e32 v181, s68, v178
	v_lshl_add_u64 v[186:187], s[22:23], 0, v[0:1]
	s_mov_b32 m0, s65
	ds_read_b128 v[230:233], v181
	ds_read_b128 v[234:237], v181 offset:1024
	ds_read_b128 v[238:241], v181 offset:2048
	ds_read_b128 v[242:245], v181 offset:3072
	global_load_lds_dwordx4 v[186:187], off
	s_add_i32 m0, s65, 0x2000
	v_lshl_add_u64 v[246:247], s[22:23], 0, v[166:167]
	global_load_lds_dwordx4 v[246:247], off
	s_barrier
	s_waitcnt lgkmcnt(0)
	v_mfma_f32_16x16x32_bf16 v[118:121], v[230:233], v[172:175], v[118:121]
	v_mfma_f32_16x16x32_bf16 v[110:113], v[238:241], v[172:175], v[110:113]
	v_mfma_f32_16x16x32_bf16 v[102:105], v[230:233], v[206:209], v[102:105]
	v_mfma_f32_16x16x32_bf16 v[94:97], v[238:241], v[206:209], v[94:97]
	v_mfma_f32_16x16x32_bf16 v[86:89], v[230:233], v[214:217], v[86:89]
	v_mfma_f32_16x16x32_bf16 v[78:81], v[238:241], v[214:217], v[78:81]
	v_mfma_f32_16x16x32_bf16 v[70:73], v[230:233], v[222:225], v[70:73]
	v_mfma_f32_16x16x32_bf16 v[66:69], v[238:241], v[222:225], v[66:69]
	v_mfma_f32_16x16x32_bf16 v[118:121], v[234:237], v[182:185], v[118:121]
	v_mfma_f32_16x16x32_bf16 v[110:113], v[242:245], v[182:185], v[110:113]
	v_mfma_f32_16x16x32_bf16 v[102:105], v[234:237], v[210:213], v[102:105]
	v_mfma_f32_16x16x32_bf16 v[94:97], v[242:245], v[210:213], v[94:97]
	v_mfma_f32_16x16x32_bf16 v[86:89], v[234:237], v[218:221], v[86:89]
	v_mfma_f32_16x16x32_bf16 v[78:81], v[242:245], v[218:221], v[78:81]
	v_mfma_f32_16x16x32_bf16 v[70:73], v[234:237], v[226:229], v[70:73]
	v_mfma_f32_16x16x32_bf16 v[66:69], v[242:245], v[226:229], v[66:69]
	s_barrier
	s_mov_b32 m0, s47
	v_lshl_add_u64 v[248:249], s[48:49], 0, v[162:163]
	ds_read_b128 v[172:175], v180 offset:16384
	ds_read_b128 v[182:185], v180 offset:17408
	ds_read_b128 v[206:209], v180 offset:18432
	ds_read_b128 v[210:213], v180 offset:19456
	ds_read_b128 v[214:217], v180 offset:20480
	ds_read_b128 v[218:221], v180 offset:21504
	ds_read_b128 v[222:225], v180 offset:22528
	ds_read_b128 v[226:229], v180 offset:23552
	global_load_lds_dwordx4 v[248:249], off
	s_mov_b32 m0, s50
	v_lshl_add_u64 v[250:251], s[48:49], 0, v[164:165]
	global_load_lds_dwordx4 v[250:251], off
	s_barrier
	s_waitcnt lgkmcnt(0)
	v_mfma_f32_16x16x32_bf16 v[62:65], v[130:133], v[172:175], v[62:65]
	v_mfma_f32_16x16x32_bf16 v[58:61], v[138:141], v[172:175], v[58:61]
	v_mfma_f32_16x16x32_bf16 v[50:53], v[130:133], v[206:209], v[50:53]
	v_mfma_f32_16x16x32_bf16 v[42:45], v[138:141], v[206:209], v[42:45]
	v_mfma_f32_16x16x32_bf16 v[34:37], v[130:133], v[214:217], v[34:37]
	v_mfma_f32_16x16x32_bf16 v[26:29], v[138:141], v[214:217], v[26:29]
	v_mfma_f32_16x16x32_bf16 v[18:21], v[130:133], v[222:225], v[18:21]
	v_mfma_f32_16x16x32_bf16 v[10:13], v[138:141], v[222:225], v[10:13]
	v_mfma_f32_16x16x32_bf16 v[62:65], v[134:137], v[182:185], v[62:65]
	v_mfma_f32_16x16x32_bf16 v[58:61], v[142:145], v[182:185], v[58:61]
	v_mfma_f32_16x16x32_bf16 v[50:53], v[134:137], v[210:213], v[50:53]
	v_mfma_f32_16x16x32_bf16 v[42:45], v[142:145], v[210:213], v[42:45]
	v_mfma_f32_16x16x32_bf16 v[34:37], v[134:137], v[218:221], v[34:37]
	v_mfma_f32_16x16x32_bf16 v[26:29], v[142:145], v[218:221], v[26:29]
	v_mfma_f32_16x16x32_bf16 v[18:21], v[134:137], v[226:229], v[18:21]
	v_mfma_f32_16x16x32_bf16 v[10:13], v[142:145], v[226:229], v[10:13]
	s_barrier
	s_add_u32 s66, s22, 0x40000
	s_addc_u32 s67, s23, 0
	s_add_i32 s65, s68, s27
	s_mov_b32 m0, s65
	v_lshl_add_u64 v[130:131], s[66:67], 0, v[0:1]
	global_load_lds_dwordx4 v[130:131], off
	s_add_i32 m0, s65, 0x2000
	v_lshl_add_u64 v[130:131], s[66:67], 0, v[166:167]
	global_load_lds_dwordx4 v[130:131], off
	s_waitcnt vmcnt(6)
	s_barrier
	v_mfma_f32_16x16x32_bf16 v[54:57], v[230:233], v[172:175], v[54:57]
	v_mfma_f32_16x16x32_bf16 v[46:49], v[238:241], v[172:175], v[46:49]
	v_mfma_f32_16x16x32_bf16 v[38:41], v[230:233], v[206:209], v[38:41]
	v_mfma_f32_16x16x32_bf16 v[30:33], v[238:241], v[206:209], v[30:33]
	v_mfma_f32_16x16x32_bf16 v[22:25], v[230:233], v[214:217], v[22:25]
	v_mfma_f32_16x16x32_bf16 v[14:17], v[238:241], v[214:217], v[14:17]
	v_mfma_f32_16x16x32_bf16 v[6:9], v[230:233], v[222:225], v[6:9]
	v_mfma_f32_16x16x32_bf16 v[2:5], v[238:241], v[222:225], v[2:5]
	v_mfma_f32_16x16x32_bf16 v[54:57], v[234:237], v[182:185], v[54:57]
	v_mfma_f32_16x16x32_bf16 v[46:49], v[242:245], v[182:185], v[46:49]
	v_mfma_f32_16x16x32_bf16 v[38:41], v[234:237], v[210:213], v[38:41]
	v_mfma_f32_16x16x32_bf16 v[30:33], v[242:245], v[210:213], v[30:33]
	v_mfma_f32_16x16x32_bf16 v[22:25], v[234:237], v[218:221], v[22:25]
	v_mfma_f32_16x16x32_bf16 v[14:17], v[242:245], v[218:221], v[14:17]
	v_mfma_f32_16x16x32_bf16 v[6:9], v[234:237], v[226:229], v[6:9]
	v_mfma_f32_16x16x32_bf16 v[2:5], v[242:245], v[226:229], v[2:5]
	s_barrier
	s_add_i32 s65, 0, 0x18000
	v_add_u32_e32 v142, s65, v178
	ds_read_b128 v[130:133], v142
	ds_read_b128 v[134:137], v142 offset:1024
	ds_read_b128 v[138:141], v142 offset:2048
	ds_read_b128 v[142:145], v142 offset:3072
	s_add_u32 s48, s48, 0x40000
	s_addc_u32 s49, s49, 0
	s_mov_b32 m0, s51
	v_lshl_add_u64 v[230:231], s[48:49], 0, v[162:163]
	ds_read_b128 v[172:175], v180 offset:32768
	ds_read_b128 v[182:185], v180 offset:33792
	ds_read_b128 v[206:209], v180 offset:34816
	ds_read_b128 v[210:213], v180 offset:35840
	ds_read_b128 v[214:217], v180 offset:36864
	ds_read_b128 v[218:221], v180 offset:37888
	ds_read_b128 v[222:225], v180 offset:38912
	ds_read_b128 v[226:229], v180 offset:39936
	global_load_lds_dwordx4 v[230:231], off
	s_mov_b32 m0, s54
	v_lshl_add_u64 v[230:231], s[48:49], 0, v[164:165]
	global_load_lds_dwordx4 v[230:231], off
	s_waitcnt lgkmcnt(8)
	s_barrier
	s_waitcnt lgkmcnt(0)
	v_mfma_f32_16x16x32_bf16 v[126:129], v[130:133], v[172:175], v[126:129]
	v_mfma_f32_16x16x32_bf16 v[122:125], v[138:141], v[172:175], v[122:125]
	v_mfma_f32_16x16x32_bf16 v[114:117], v[130:133], v[206:209], v[114:117]
	v_mfma_f32_16x16x32_bf16 v[106:109], v[138:141], v[206:209], v[106:109]
	v_mfma_f32_16x16x32_bf16 v[98:101], v[130:133], v[214:217], v[98:101]
	v_mfma_f32_16x16x32_bf16 v[90:93], v[138:141], v[214:217], v[90:93]
	v_mfma_f32_16x16x32_bf16 v[82:85], v[130:133], v[222:225], v[82:85]
	v_mfma_f32_16x16x32_bf16 v[74:77], v[138:141], v[222:225], v[74:77]
	v_mfma_f32_16x16x32_bf16 v[126:129], v[134:137], v[182:185], v[126:129]
	v_mfma_f32_16x16x32_bf16 v[122:125], v[142:145], v[182:185], v[122:125]
	v_mfma_f32_16x16x32_bf16 v[114:117], v[134:137], v[210:213], v[114:117]
	v_mfma_f32_16x16x32_bf16 v[106:109], v[142:145], v[210:213], v[106:109]
	v_mfma_f32_16x16x32_bf16 v[98:101], v[134:137], v[218:221], v[98:101]
	v_mfma_f32_16x16x32_bf16 v[90:93], v[142:145], v[218:221], v[90:93]
	v_mfma_f32_16x16x32_bf16 v[82:85], v[134:137], v[226:229], v[82:85]
	v_mfma_f32_16x16x32_bf16 v[74:77], v[142:145], v[226:229], v[74:77]
	s_barrier
	s_add_i32 s48, 0, 0x1c000
	s_add_i32 s49, s65, s27
	v_add_u32_e32 v181, s48, v178
	v_lshl_add_u64 v[186:187], v[186:187], 0, s[94:95]
	s_mov_b32 m0, s49
	ds_read_b128 v[230:233], v181
	ds_read_b128 v[234:237], v181 offset:1024
	ds_read_b128 v[238:241], v181 offset:2048
	ds_read_b128 v[242:245], v181 offset:3072
	global_load_lds_dwordx4 v[186:187], off
	s_add_i32 m0, s49, 0x2000
	v_lshl_add_u64 v[186:187], v[246:247], 0, s[94:95]
	global_load_lds_dwordx4 v[186:187], off
	s_barrier
	s_waitcnt lgkmcnt(0)
	v_mfma_f32_16x16x32_bf16 v[118:121], v[230:233], v[172:175], v[118:121]
	v_mfma_f32_16x16x32_bf16 v[110:113], v[238:241], v[172:175], v[110:113]
	v_mfma_f32_16x16x32_bf16 v[102:105], v[230:233], v[206:209], v[102:105]
	v_mfma_f32_16x16x32_bf16 v[94:97], v[238:241], v[206:209], v[94:97]
	v_mfma_f32_16x16x32_bf16 v[86:89], v[230:233], v[214:217], v[86:89]
	v_mfma_f32_16x16x32_bf16 v[78:81], v[238:241], v[214:217], v[78:81]
	v_mfma_f32_16x16x32_bf16 v[70:73], v[230:233], v[222:225], v[70:73]
	v_mfma_f32_16x16x32_bf16 v[66:69], v[238:241], v[222:225], v[66:69]
	v_mfma_f32_16x16x32_bf16 v[118:121], v[234:237], v[182:185], v[118:121]
	v_mfma_f32_16x16x32_bf16 v[110:113], v[242:245], v[182:185], v[110:113]
	v_mfma_f32_16x16x32_bf16 v[102:105], v[234:237], v[210:213], v[102:105]
	v_mfma_f32_16x16x32_bf16 v[94:97], v[242:245], v[210:213], v[94:97]
	v_mfma_f32_16x16x32_bf16 v[86:89], v[234:237], v[218:221], v[86:89]
	v_mfma_f32_16x16x32_bf16 v[78:81], v[242:245], v[218:221], v[78:81]
	v_mfma_f32_16x16x32_bf16 v[70:73], v[234:237], v[226:229], v[70:73]
	v_mfma_f32_16x16x32_bf16 v[66:69], v[242:245], v[226:229], v[66:69]
	s_barrier
	s_mov_b32 m0, s55
	v_lshl_add_u64 v[186:187], v[248:249], 0, s[94:95]
	ds_read_b128 v[172:175], v180 offset:49152
	ds_read_b128 v[182:185], v180 offset:50176
	ds_read_b128 v[206:209], v180 offset:51200
	ds_read_b128 v[210:213], v180 offset:52224
	ds_read_b128 v[214:217], v180 offset:53248
	ds_read_b128 v[218:221], v180 offset:54272
	ds_read_b128 v[222:225], v180 offset:55296
	ds_read_b128 v[226:229], v180 offset:56320
	global_load_lds_dwordx4 v[186:187], off
	s_mov_b32 m0, s56
	v_lshl_add_u64 v[186:187], v[250:251], 0, s[94:95]
	global_load_lds_dwordx4 v[186:187], off
	s_barrier
	s_waitcnt lgkmcnt(0)
	v_mfma_f32_16x16x32_bf16 v[62:65], v[130:133], v[172:175], v[62:65]
	v_mfma_f32_16x16x32_bf16 v[58:61], v[138:141], v[172:175], v[58:61]
	v_mfma_f32_16x16x32_bf16 v[50:53], v[130:133], v[206:209], v[50:53]
	v_mfma_f32_16x16x32_bf16 v[42:45], v[138:141], v[206:209], v[42:45]
	v_mfma_f32_16x16x32_bf16 v[34:37], v[130:133], v[214:217], v[34:37]
	v_mfma_f32_16x16x32_bf16 v[26:29], v[138:141], v[214:217], v[26:29]
	v_mfma_f32_16x16x32_bf16 v[18:21], v[130:133], v[222:225], v[18:21]
	v_mfma_f32_16x16x32_bf16 v[10:13], v[138:141], v[222:225], v[10:13]
	v_mfma_f32_16x16x32_bf16 v[62:65], v[134:137], v[182:185], v[62:65]
	v_mfma_f32_16x16x32_bf16 v[58:61], v[142:145], v[182:185], v[58:61]
	v_mfma_f32_16x16x32_bf16 v[50:53], v[134:137], v[210:213], v[50:53]
	v_mfma_f32_16x16x32_bf16 v[42:45], v[142:145], v[210:213], v[42:45]
	v_mfma_f32_16x16x32_bf16 v[34:37], v[134:137], v[218:221], v[34:37]
	v_mfma_f32_16x16x32_bf16 v[26:29], v[142:145], v[218:221], v[26:29]
	v_mfma_f32_16x16x32_bf16 v[18:21], v[134:137], v[226:229], v[18:21]
	v_mfma_f32_16x16x32_bf16 v[10:13], v[142:145], v[226:229], v[10:13]
	s_barrier
	s_add_u32 s22, s22, 0x40080
	s_addc_u32 s23, s23, 0
	s_add_i32 s48, s48, s27
	s_mov_b32 m0, s48
	v_lshl_add_u64 v[130:131], s[22:23], 0, v[0:1]
	global_load_lds_dwordx4 v[130:131], off
	s_add_i32 m0, s48, 0x2000
	v_lshl_add_u64 v[130:131], s[22:23], 0, v[166:167]
	global_load_lds_dwordx4 v[130:131], off
	s_waitcnt vmcnt(6)
	s_barrier
	v_mfma_f32_16x16x32_bf16 v[54:57], v[230:233], v[172:175], v[54:57]
	v_mfma_f32_16x16x32_bf16 v[46:49], v[238:241], v[172:175], v[46:49]
	v_mfma_f32_16x16x32_bf16 v[38:41], v[230:233], v[206:209], v[38:41]
	v_mfma_f32_16x16x32_bf16 v[30:33], v[238:241], v[206:209], v[30:33]
	v_mfma_f32_16x16x32_bf16 v[22:25], v[230:233], v[214:217], v[22:25]
	v_mfma_f32_16x16x32_bf16 v[14:17], v[238:241], v[214:217], v[14:17]
	v_mfma_f32_16x16x32_bf16 v[6:9], v[230:233], v[222:225], v[6:9]
	v_mfma_f32_16x16x32_bf16 v[2:5], v[238:241], v[222:225], v[2:5]
	v_mfma_f32_16x16x32_bf16 v[54:57], v[234:237], v[182:185], v[54:57]
	v_mfma_f32_16x16x32_bf16 v[46:49], v[242:245], v[182:185], v[46:49]
	v_mfma_f32_16x16x32_bf16 v[38:41], v[234:237], v[210:213], v[38:41]
	v_mfma_f32_16x16x32_bf16 v[30:33], v[242:245], v[210:213], v[30:33]
	v_mfma_f32_16x16x32_bf16 v[22:25], v[234:237], v[218:221], v[22:25]
	v_mfma_f32_16x16x32_bf16 v[14:17], v[242:245], v[218:221], v[14:17]
	v_mfma_f32_16x16x32_bf16 v[6:9], v[234:237], v[226:229], v[6:9]
	v_mfma_f32_16x16x32_bf16 v[2:5], v[242:245], v[226:229], v[2:5]
	s_barrier
	s_add_i32 s64, s64, 2
	s_add_u32 s0, s0, 0x100
	s_addc_u32 s1, s1, 0
	s_add_u32 s62, s62, 0x100
	s_addc_u32 s63, s63, 0
	s_cmp_gt_u32 s64, 13
	s_cbranch_scc0 .LBB0_57
	v_lshl_or_b32 v172, s59, 8, v179
	v_ashrrev_i32_e32 v173, 31, v172
	v_cndmask_b32_e64 v131, 0, 1, s[2:3]
	v_lshl_add_u64 v[174:175], v[172:173], 2, s[8:9]
	v_mov_b32_e32 v130, 0
	v_cmp_ne_u32_e64 s[0:1], 1, v131
	s_andn2_b64 vcc, exec, s[2:3]
	v_mov_b32_e32 v134, 0
	v_mov_b32_e32 v135, 0
	v_mov_b32_e32 v136, 0
	v_mov_b32_e32 v137, 0
	s_cbranch_vccnz .LBB0_60
	global_load_dwordx4 v[134:137], v[174:175], off

.Lkprio_4:
.LBB0_95:
	s_add_u32 s22, s8, 0xfffc0080
	s_addc_u32 s23, s9, -1
	s_add_i32 s63, 0, 0x10000
	v_add_u32_e32 v78, s63, v178
	ds_read_b128 v[58:61], v78
	ds_read_b128 v[66:69], v78 offset:1024
	ds_read_b128 v[74:77], v78 offset:2048
	ds_read_b128 v[78:81], v78 offset:3072
	s_cmp_eq_u32 s49, 12
	s_cselect_b32 s29, s25, s23
	s_cselect_b32 s28, s26, s22
	s_cselect_b32 s23, s27, s47
	s_cselect_b32 s22, s30, s31
	v_lshl_add_u64 v[186:187], s[8:9], 0, v[168:169]
	s_add_i32 m0, s3, 0xc000
	ds_read_b128 v[172:175], v180
	ds_read_b128 v[182:185], v180 offset:1024
	ds_read_b128 v[206:209], v180 offset:2048
	ds_read_b128 v[210:213], v180 offset:3072
	ds_read_b128 v[214:217], v180 offset:4096
	ds_read_b128 v[218:221], v180 offset:5120
	ds_read_b128 v[222:225], v180 offset:6144
	ds_read_b128 v[226:229], v180 offset:7168
	global_load_lds_dwordx4 v[186:187], off
	s_add_i32 m0, s3, 0xe000
	v_lshl_add_u64 v[186:187], s[8:9], 0, v[170:171]
	global_load_lds_dwordx4 v[186:187], off
	s_waitcnt lgkmcnt(8)
	s_barrier
	s_waitcnt lgkmcnt(0)
	v_mfma_f32_16x16x32_bf16 v[142:145], v[58:61], v[172:175], v[142:145]
	v_mfma_f32_16x16x32_bf16 v[138:141], v[74:77], v[172:175], v[138:141]
	v_mfma_f32_16x16x32_bf16 v[126:129], v[58:61], v[206:209], v[126:129]
	v_mfma_f32_16x16x32_bf16 v[118:121], v[74:77], v[206:209], v[118:121]
	v_mfma_f32_16x16x32_bf16 v[110:113], v[58:61], v[214:217], v[110:113]
	v_mfma_f32_16x16x32_bf16 v[102:105], v[74:77], v[214:217], v[102:105]
	v_mfma_f32_16x16x32_bf16 v[94:97], v[58:61], v[222:225], v[94:97]
	v_mfma_f32_16x16x32_bf16 v[86:89], v[74:77], v[222:225], v[86:89]
	v_mfma_f32_16x16x32_bf16 v[142:145], v[66:69], v[182:185], v[142:145]
	v_mfma_f32_16x16x32_bf16 v[138:141], v[78:81], v[182:185], v[138:141]
	v_mfma_f32_16x16x32_bf16 v[126:129], v[66:69], v[210:213], v[126:129]
	v_mfma_f32_16x16x32_bf16 v[118:121], v[78:81], v[210:213], v[118:121]
	v_mfma_f32_16x16x32_bf16 v[110:113], v[66:69], v[218:221], v[110:113]
	v_mfma_f32_16x16x32_bf16 v[102:105], v[78:81], v[218:221], v[102:105]
	v_mfma_f32_16x16x32_bf16 v[94:97], v[66:69], v[226:229], v[94:97]
	v_mfma_f32_16x16x32_bf16 v[86:89], v[78:81], v[226:229], v[86:89]
	s_barrier
	s_add_i32 s66, 0, 0x14000
	s_add_i32 s63, s63, s37
	v_add_u32_e32 v181, s66, v178
	v_lshl_add_u64 v[186:187], s[22:23], 0, v[0:1]
	s_mov_b32 m0, s63
	ds_read_b128 v[230:233], v181
	ds_read_b128 v[234:237], v181 offset:1024
	ds_read_b128 v[238:241], v181 offset:2048
	ds_read_b128 v[242:245], v181 offset:3072
	global_load_lds_dwordx4 v[186:187], off
	s_add_i32 m0, s63, 0x2000
	v_lshl_add_u64 v[246:247], s[22:23], 0, v[166:167]
	global_load_lds_dwordx4 v[246:247], off
	s_barrier
	s_waitcnt lgkmcnt(0)
	v_mfma_f32_16x16x32_bf16 v[134:137], v[230:233], v[172:175], v[134:137]
	v_mfma_f32_16x16x32_bf16 v[130:133], v[238:241], v[172:175], v[130:133]
	v_mfma_f32_16x16x32_bf16 v[122:125], v[230:233], v[206:209], v[122:125]
	v_mfma_f32_16x16x32_bf16 v[114:117], v[238:241], v[206:209], v[114:117]
	v_mfma_f32_16x16x32_bf16 v[106:109], v[230:233], v[214:217], v[106:109]
	v_mfma_f32_16x16x32_bf16 v[98:101], v[238:241], v[214:217], v[98:101]
	v_mfma_f32_16x16x32_bf16 v[90:93], v[230:233], v[222:225], v[90:93]
	v_mfma_f32_16x16x32_bf16 v[82:85], v[238:241], v[222:225], v[82:85]
	v_mfma_f32_16x16x32_bf16 v[134:137], v[234:237], v[182:185], v[134:137]
	v_mfma_f32_16x16x32_bf16 v[130:133], v[242:245], v[182:185], v[130:133]
	v_mfma_f32_16x16x32_bf16 v[122:125], v[234:237], v[210:213], v[122:125]
	v_mfma_f32_16x16x32_bf16 v[114:117], v[242:245], v[210:213], v[114:117]
	v_mfma_f32_16x16x32_bf16 v[106:109], v[234:237], v[218:221], v[106:109]
	v_mfma_f32_16x16x32_bf16 v[98:101], v[242:245], v[218:221], v[98:101]
	v_mfma_f32_16x16x32_bf16 v[90:93], v[234:237], v[226:229], v[90:93]
	v_mfma_f32_16x16x32_bf16 v[82:85], v[242:245], v[226:229], v[82:85]
	s_barrier
	s_mov_b32 m0, s3
	v_lshl_add_u64 v[248:249], s[28:29], 0, v[162:163]
	ds_read_b128 v[172:175], v180 offset:16384
	ds_read_b128 v[182:185], v180 offset:17408
	ds_read_b128 v[206:209], v180 offset:18432
	ds_read_b128 v[210:213], v180 offset:19456
	ds_read_b128 v[214:217], v180 offset:20480
	ds_read_b128 v[218:221], v180 offset:21504
	ds_read_b128 v[222:225], v180 offset:22528
	ds_read_b128 v[226:229], v180 offset:23552
	global_load_lds_dwordx4 v[248:249], off
	s_mov_b32 m0, s56
	v_lshl_add_u64 v[250:251], s[28:29], 0, v[164:165]
	global_load_lds_dwordx4 v[250:251], off
	s_barrier
	s_waitcnt lgkmcnt(0)
	v_mfma_f32_16x16x32_bf16 v[70:73], v[58:61], v[172:175], v[70:73]
	v_mfma_f32_16x16x32_bf16 v[54:57], v[74:77], v[172:175], v[54:57]
	v_mfma_f32_16x16x32_bf16 v[46:49], v[58:61], v[206:209], v[46:49]
	v_mfma_f32_16x16x32_bf16 v[38:41], v[74:77], v[206:209], v[38:41]
	v_mfma_f32_16x16x32_bf16 v[30:33], v[58:61], v[214:217], v[30:33]
	v_mfma_f32_16x16x32_bf16 v[22:25], v[74:77], v[214:217], v[22:25]
	v_mfma_f32_16x16x32_bf16 v[14:17], v[58:61], v[222:225], v[14:17]
	v_mfma_f32_16x16x32_bf16 v[6:9], v[74:77], v[222:225], v[6:9]
	v_mfma_f32_16x16x32_bf16 v[70:73], v[66:69], v[182:185], v[70:73]
	v_mfma_f32_16x16x32_bf16 v[54:57], v[78:81], v[182:185], v[54:57]
	v_mfma_f32_16x16x32_bf16 v[46:49], v[66:69], v[210:213], v[46:49]
	v_mfma_f32_16x16x32_bf16 v[38:41], v[78:81], v[210:213], v[38:41]
	v_mfma_f32_16x16x32_bf16 v[30:33], v[66:69], v[218:221], v[30:33]
	v_mfma_f32_16x16x32_bf16 v[22:25], v[78:81], v[218:221], v[22:25]
	v_mfma_f32_16x16x32_bf16 v[14:17], v[66:69], v[226:229], v[14:17]
	v_mfma_f32_16x16x32_bf16 v[6:9], v[78:81], v[226:229], v[6:9]
	s_barrier
	s_add_u32 s64, s22, 0x40000
	s_addc_u32 s65, s23, 0
	s_add_i32 s63, s66, s37
	s_mov_b32 m0, s63
	v_lshl_add_u64 v[58:59], s[64:65], 0, v[0:1]
	global_load_lds_dwordx4 v[58:59], off
	s_add_i32 m0, s63, 0x2000
	v_lshl_add_u64 v[58:59], s[64:65], 0, v[166:167]
	global_load_lds_dwordx4 v[58:59], off
	s_waitcnt vmcnt(6)
	s_barrier
	v_mfma_f32_16x16x32_bf16 v[50:53], v[238:241], v[172:175], v[50:53]
	v_mfma_f32_16x16x32_bf16 v[42:45], v[230:233], v[206:209], v[42:45]
	v_mfma_f32_16x16x32_bf16 v[34:37], v[238:241], v[206:209], v[34:37]
	v_mfma_f32_16x16x32_bf16 v[26:29], v[230:233], v[214:217], v[26:29]
	v_mfma_f32_16x16x32_bf16 v[18:21], v[238:241], v[214:217], v[18:21]
	v_mfma_f32_16x16x32_bf16 v[10:13], v[230:233], v[222:225], v[10:13]
	v_mfma_f32_16x16x32_bf16 v[2:5], v[238:241], v[222:225], v[2:5]
	v_mfma_f32_16x16x32_bf16 v[58:61], v[230:233], v[172:175], v[62:65]
	v_mfma_f32_16x16x32_bf16 v[50:53], v[242:245], v[182:185], v[50:53]
	v_mfma_f32_16x16x32_bf16 v[42:45], v[234:237], v[210:213], v[42:45]
	v_mfma_f32_16x16x32_bf16 v[34:37], v[242:245], v[210:213], v[34:37]
	v_mfma_f32_16x16x32_bf16 v[26:29], v[234:237], v[218:221], v[26:29]
	v_mfma_f32_16x16x32_bf16 v[18:21], v[242:245], v[218:221], v[18:21]
	v_mfma_f32_16x16x32_bf16 v[10:13], v[234:237], v[226:229], v[10:13]
	v_mfma_f32_16x16x32_bf16 v[2:5], v[242:245], v[226:229], v[2:5]
	v_mfma_f32_16x16x32_bf16 v[58:61], v[234:237], v[182:185], v[58:61]
	s_barrier
	s_add_i32 s63, 0, 0x18000
	v_add_u32_e32 v78, s63, v178
	ds_read_b128 v[62:65], v78
	ds_read_b128 v[66:69], v78 offset:1024
	ds_read_b128 v[74:77], v78 offset:2048
	ds_read_b128 v[78:81], v78 offset:3072
	s_add_u32 s28, s28, 0x40000
	s_addc_u32 s29, s29, 0
	s_mov_b32 m0, s57
	v_lshl_add_u64 v[230:231], s[28:29], 0, v[162:163]
	ds_read_b128 v[172:175], v180 offset:32768
	ds_read_b128 v[182:185], v180 offset:33792
	ds_read_b128 v[206:209], v180 offset:34816
	ds_read_b128 v[210:213], v180 offset:35840
	ds_read_b128 v[214:217], v180 offset:36864
	ds_read_b128 v[218:221], v180 offset:37888
	ds_read_b128 v[222:225], v180 offset:38912
	ds_read_b128 v[226:229], v180 offset:39936
	global_load_lds_dwordx4 v[230:231], off
	s_mov_b32 m0, s58
	v_lshl_add_u64 v[230:231], s[28:29], 0, v[164:165]
	global_load_lds_dwordx4 v[230:231], off
	s_waitcnt lgkmcnt(8)
	s_barrier
	s_waitcnt lgkmcnt(0)
	v_mfma_f32_16x16x32_bf16 v[142:145], v[62:65], v[172:175], v[142:145]
	v_mfma_f32_16x16x32_bf16 v[138:141], v[74:77], v[172:175], v[138:141]
	v_mfma_f32_16x16x32_bf16 v[126:129], v[62:65], v[206:209], v[126:129]
	v_mfma_f32_16x16x32_bf16 v[118:121], v[74:77], v[206:209], v[118:121]
	v_mfma_f32_16x16x32_bf16 v[110:113], v[62:65], v[214:217], v[110:113]
	v_mfma_f32_16x16x32_bf16 v[102:105], v[74:77], v[214:217], v[102:105]
	v_mfma_f32_16x16x32_bf16 v[94:97], v[62:65], v[222:225], v[94:97]
	v_mfma_f32_16x16x32_bf16 v[86:89], v[74:77], v[222:225], v[86:89]
	v_mfma_f32_16x16x32_bf16 v[142:145], v[66:69], v[182:185], v[142:145]
	v_mfma_f32_16x16x32_bf16 v[138:141], v[78:81], v[182:185], v[138:141]
	v_mfma_f32_16x16x32_bf16 v[126:129], v[66:69], v[210:213], v[126:129]
	v_mfma_f32_16x16x32_bf16 v[118:121], v[78:81], v[210:213], v[118:121]
	v_mfma_f32_16x16x32_bf16 v[110:113], v[66:69], v[218:221], v[110:113]
	v_mfma_f32_16x16x32_bf16 v[102:105], v[78:81], v[218:221], v[102:105]
	v_mfma_f32_16x16x32_bf16 v[94:97], v[66:69], v[226:229], v[94:97]
	v_mfma_f32_16x16x32_bf16 v[86:89], v[78:81], v[226:229], v[86:89]
	s_barrier
	s_add_i32 s28, 0, 0x1c000
	s_add_i32 s29, s63, s37
	v_add_u32_e32 v181, s28, v178
	v_lshl_add_u64 v[186:187], v[186:187], 0, s[94:95]
	s_mov_b32 m0, s29
	ds_read_b128 v[230:233], v181
	ds_read_b128 v[234:237], v181 offset:1024
	ds_read_b128 v[238:241], v181 offset:2048
	ds_read_b128 v[242:245], v181 offset:3072
	global_load_lds_dwordx4 v[186:187], off
	s_add_i32 m0, s29, 0x2000
	v_lshl_add_u64 v[186:187], v[246:247], 0, s[94:95]
	global_load_lds_dwordx4 v[186:187], off
	s_barrier
	s_waitcnt lgkmcnt(0)
	v_mfma_f32_16x16x32_bf16 v[134:137], v[230:233], v[172:175], v[134:137]
	v_mfma_f32_16x16x32_bf16 v[130:133], v[238:241], v[172:175], v[130:133]
	v_mfma_f32_16x16x32_bf16 v[122:125], v[230:233], v[206:209], v[122:125]
	v_mfma_f32_16x16x32_bf16 v[114:117], v[238:241], v[206:209], v[114:117]
	v_mfma_f32_16x16x32_bf16 v[106:109], v[230:233], v[214:217], v[106:109]
	v_mfma_f32_16x16x32_bf16 v[98:101], v[238:241], v[214:217], v[98:101]
	v_mfma_f32_16x16x32_bf16 v[90:93], v[230:233], v[222:225], v[90:93]
	v_mfma_f32_16x16x32_bf16 v[82:85], v[238:241], v[222:225], v[82:85]
	v_mfma_f32_16x16x32_bf16 v[134:137], v[234:237], v[182:185], v[134:137]
	v_mfma_f32_16x16x32_bf16 v[130:133], v[242:245], v[182:185], v[130:133]
	v_mfma_f32_16x16x32_bf16 v[122:125], v[234:237], v[210:213], v[122:125]
	v_mfma_f32_16x16x32_bf16 v[114:117], v[242:245], v[210:213], v[114:117]
	v_mfma_f32_16x16x32_bf16 v[106:109], v[234:237], v[218:221], v[106:109]
	v_mfma_f32_16x16x32_bf16 v[98:101], v[242:245], v[218:221], v[98:101]
	v_mfma_f32_16x16x32_bf16 v[90:93], v[234:237], v[226:229], v[90:93]
	v_mfma_f32_16x16x32_bf16 v[82:85], v[242:245], v[226:229], v[82:85]
	s_barrier
	s_mov_b32 m0, s59
	v_lshl_add_u64 v[186:187], v[248:249], 0, s[94:95]
	ds_read_b128 v[172:175], v180 offset:49152
	ds_read_b128 v[182:185], v180 offset:50176
	ds_read_b128 v[206:209], v180 offset:51200
	ds_read_b128 v[210:213], v180 offset:52224
	ds_read_b128 v[214:217], v180 offset:53248
	ds_read_b128 v[218:221], v180 offset:54272
	ds_read_b128 v[222:225], v180 offset:55296
	ds_read_b128 v[226:229], v180 offset:56320
	global_load_lds_dwordx4 v[186:187], off
	s_mov_b32 m0, s60
	v_lshl_add_u64 v[186:187], v[250:251], 0, s[94:95]
	global_load_lds_dwordx4 v[186:187], off
	s_barrier
	s_waitcnt lgkmcnt(0)
	v_mfma_f32_16x16x32_bf16 v[70:73], v[62:65], v[172:175], v[70:73]
	v_mfma_f32_16x16x32_bf16 v[54:57], v[74:77], v[172:175], v[54:57]
	v_mfma_f32_16x16x32_bf16 v[46:49], v[62:65], v[206:209], v[46:49]
	v_mfma_f32_16x16x32_bf16 v[38:41], v[74:77], v[206:209], v[38:41]
	v_mfma_f32_16x16x32_bf16 v[30:33], v[62:65], v[214:217], v[30:33]
	v_mfma_f32_16x16x32_bf16 v[22:25], v[74:77], v[214:217], v[22:25]
	v_mfma_f32_16x16x32_bf16 v[14:17], v[62:65], v[222:225], v[14:17]
	v_mfma_f32_16x16x32_bf16 v[6:9], v[74:77], v[222:225], v[6:9]
	v_mfma_f32_16x16x32_bf16 v[70:73], v[66:69], v[182:185], v[70:73]
	v_mfma_f32_16x16x32_bf16 v[54:57], v[78:81], v[182:185], v[54:57]
	v_mfma_f32_16x16x32_bf16 v[46:49], v[66:69], v[210:213], v[46:49]
	v_mfma_f32_16x16x32_bf16 v[38:41], v[78:81], v[210:213], v[38:41]
	v_mfma_f32_16x16x32_bf16 v[30:33], v[66:69], v[218:221], v[30:33]
	v_mfma_f32_16x16x32_bf16 v[22:25], v[78:81], v[218:221], v[22:25]
	v_mfma_f32_16x16x32_bf16 v[14:17], v[66:69], v[226:229], v[14:17]
	v_mfma_f32_16x16x32_bf16 v[6:9], v[78:81], v[226:229], v[6:9]
	s_barrier
	s_add_u32 s22, s22, 0x40080
	s_addc_u32 s23, s23, 0
	s_add_i32 s28, s28, s37
	s_mov_b32 m0, s28
	v_lshl_add_u64 v[62:63], s[22:23], 0, v[0:1]
	global_load_lds_dwordx4 v[62:63], off
	s_add_i32 m0, s28, 0x2000
	v_lshl_add_u64 v[62:63], s[22:23], 0, v[166:167]
	global_load_lds_dwordx4 v[62:63], off
	s_waitcnt vmcnt(6)
	s_barrier
	v_mfma_f32_16x16x32_bf16 v[58:61], v[230:233], v[172:175], v[58:61]
	v_mfma_f32_16x16x32_bf16 v[50:53], v[238:241], v[172:175], v[50:53]
	v_mfma_f32_16x16x32_bf16 v[42:45], v[230:233], v[206:209], v[42:45]
	v_mfma_f32_16x16x32_bf16 v[34:37], v[238:241], v[206:209], v[34:37]
	v_mfma_f32_16x16x32_bf16 v[26:29], v[230:233], v[214:217], v[26:29]
	v_mfma_f32_16x16x32_bf16 v[18:21], v[238:241], v[214:217], v[18:21]
	v_mfma_f32_16x16x32_bf16 v[10:13], v[230:233], v[222:225], v[10:13]
	v_mfma_f32_16x16x32_bf16 v[2:5], v[238:241], v[222:225], v[2:5]
	v_mfma_f32_16x16x32_bf16 v[62:65], v[234:237], v[182:185], v[58:61]
	v_mfma_f32_16x16x32_bf16 v[50:53], v[242:245], v[182:185], v[50:53]
	v_mfma_f32_16x16x32_bf16 v[42:45], v[234:237], v[210:213], v[42:45]
	v_mfma_f32_16x16x32_bf16 v[34:37], v[242:245], v[210:213], v[34:37]
	v_mfma_f32_16x16x32_bf16 v[26:29], v[234:237], v[218:221], v[26:29]
	v_mfma_f32_16x16x32_bf16 v[18:21], v[242:245], v[218:221], v[18:21]
	v_mfma_f32_16x16x32_bf16 v[10:13], v[234:237], v[226:229], v[10:13]
	v_mfma_f32_16x16x32_bf16 v[2:5], v[242:245], v[226:229], v[2:5]
	s_barrier
	s_add_i32 s49, s49, 2
	s_add_u32 s8, s8, 0x100
	s_addc_u32 s9, s9, 0
	s_add_u32 s31, s31, 0x100
	s_addc_u32 s47, s47, 0
	s_cmp_gt_u32 s49, 13
	s_cbranch_scc0 .LBB0_95
	v_lshl_or_b32 v172, s24, 7, v179
	v_ashrrev_i32_e32 v173, 31, v172
	v_lshlrev_b64 v[58:59], 2, v[172:173]
	v_lshl_add_u64 v[60:61], s[40:41], 0, v[58:59]
	v_lshl_add_u64 v[74:75], s[44:45], 0, v[58:59]
	global_load_dwordx4 v[66:69], v[60:61], off offset:16
	global_load_dwordx4 v[78:81], v[60:61], off
	s_nop 0
	global_load_dwordx4 v[58:61], v[74:75], off offset:16
	s_nop 0
	global_load_dwordx4 v[74:77], v[74:75], off
	v_lshl_add_u32 v174, s2, 8, v177
	v_ashrrev_i32_e32 v175, 31, v174
	v_lshl_add_u64 v[172:173], v[172:173], 1, s[20:21]
	v_lshlrev_b64 v[182:183], 11, v[174:175]
	s_mov_b32 s2, 0x50000
	s_mov_b32 s24, s46
	s_mov_b64 s[22:23], s[54:55]
	s_mov_b64 s[8:9], s[50:51]
	s_waitcnt vmcnt(0)
	v_add_f32_e32 v138, v138, v66
	v_add_f32_e32 v126, v126, v78
	v_add_f32_e32 v130, v130, v58
	v_mul_f32_e32 v130, 0xbfb8aa3b, v130
	v_add_f32_e32 v131, v131, v59
	v_add_f32_e32 v122, v122, v74
	v_exp_f32_e32 v130, v130
	v_mul_f32_e32 v131, 0xbfb8aa3b, v131
	v_mul_f32_e32 v122, 0xbfb8aa3b, v122
	v_add_f32_e32 v123, v123, v75
	v_exp_f32_e32 v131, v131
	v_exp_f32_e32 v122, v122
	v_mul_f32_e32 v123, 0xbfb8aa3b, v123
	v_add_f32_e32 v124, v124, v76
	v_exp_f32_e32 v123, v123
	v_mul_f32_e32 v124, 0xbfb8aa3b, v124
	v_add_f32_e32 v125, v125, v77
	v_add_f32_e32 v114, v114, v58
	v_exp_f32_e32 v124, v124
	v_mul_f32_e32 v125, 0xbfb8aa3b, v125
	v_mul_f32_e32 v114, 0xbfb8aa3b, v114
	v_add_f32_e32 v115, v115, v59
	v_add_f32_e32 v106, v106, v74
	v_add_f32_e32 v130, 1.0, v130
	v_exp_f32_e32 v125, v125
	v_exp_f32_e32 v114, v114
	v_mul_f32_e32 v115, 0xbfb8aa3b, v115
	v_mul_f32_e32 v106, 0xbfb8aa3b, v106
	v_add_f32_e32 v107, v107, v75
	v_rcp_f32_e32 v130, v130
	v_add_f32_e32 v131, 1.0, v131
	v_add_f32_e32 v122, 1.0, v122
	v_exp_f32_e32 v115, v115
	v_exp_f32_e32 v106, v106
	v_mul_f32_e32 v107, 0xbfb8aa3b, v107
	v_add_f32_e32 v108, v108, v76
	v_rcp_f32_e32 v131, v131
	v_rcp_f32_e32 v122, v122
	v_add_f32_e32 v123, 1.0, v123
	v_exp_f32_e32 v107, v107
	v_mul_f32_e32 v108, 0xbfb8aa3b, v108
	v_add_f32_e32 v109, v109, v77
	v_add_f32_e32 v98, v98, v58
	v_rcp_f32_e32 v123, v123
	v_add_f32_e32 v124, 1.0, v124
	v_exp_f32_e32 v108, v108
	v_mul_f32_e32 v109, 0xbfb8aa3b, v109
	v_mul_f32_e32 v98, 0xbfb8aa3b, v98
	v_add_f32_e32 v99, v99, v59
	v_add_f32_e32 v90, v90, v74
	v_rcp_f32_e32 v124, v124
	v_add_f32_e32 v125, 1.0, v125
	v_add_f32_e32 v114, 1.0, v114
	v_exp_f32_e32 v109, v109
	v_exp_f32_e32 v98, v98
	v_mul_f32_e32 v99, 0xbfb8aa3b, v99
	v_mul_f32_e32 v90, 0xbfb8aa3b, v90
	v_add_f32_e32 v91, v91, v75
	v_mul_f32_e32 v138, v138, v130
	v_add_f32_e32 v130, v139, v67
	v_rcp_f32_e32 v125, v125
	v_rcp_f32_e32 v114, v114
	v_add_f32_e32 v115, 1.0, v115
	v_add_f32_e32 v106, 1.0, v106
	v_exp_f32_e32 v99, v99
	v_exp_f32_e32 v90, v90
	v_mul_f32_e32 v91, 0xbfb8aa3b, v91
	v_add_f32_e32 v92, v92, v76
	v_mul_f32_e32 v139, v130, v131
	v_add_f32_e32 v131, v132, v60
	v_mul_f32_e32 v122, v126, v122
	v_add_f32_e32 v126, v127, v79
	v_rcp_f32_e32 v115, v115
	v_rcp_f32_e32 v106, v106
	v_add_f32_e32 v107, 1.0, v107
	v_exp_f32_e32 v91, v91
	v_mul_f32_e32 v92, 0xbfb8aa3b, v92
	v_add_f32_e32 v93, v93, v77
	v_add_f32_e32 v82, v82, v58
	v_mul_f32_e32 v131, 0xbfb8aa3b, v131
	v_mul_f32_e32 v123, v126, v123
	v_add_f32_e32 v126, v128, v80
	v_rcp_f32_e32 v107, v107
	v_add_f32_e32 v108, 1.0, v108
	v_exp_f32_e32 v92, v92
	v_mul_f32_e32 v93, 0xbfb8aa3b, v93
	v_mul_f32_e32 v82, 0xbfb8aa3b, v82
	v_add_f32_e32 v83, v83, v59
	v_add_f32_e32 v50, v50, v58
	v_exp_f32_e32 v131, v131
	v_mul_f32_e32 v124, v126, v124
	v_add_f32_e32 v126, v129, v81
	v_add_f32_e32 v118, v118, v66
	v_rcp_f32_e32 v108, v108
	v_add_f32_e32 v109, 1.0, v109
	v_add_f32_e32 v98, 1.0, v98
	v_exp_f32_e32 v93, v93
	v_exp_f32_e32 v82, v82
	v_mul_f32_e32 v83, 0xbfb8aa3b, v83
	v_mul_f32_e32 v50, 0xbfb8aa3b, v50
	v_add_f32_e32 v51, v51, v59
	v_mul_f32_e32 v125, v126, v125
	v_mul_f32_e32 v126, v118, v114
	v_add_f32_e32 v114, v119, v67
	v_add_f32_e32 v110, v110, v78
	v_rcp_f32_e32 v109, v109
	v_rcp_f32_e32 v98, v98
	v_add_f32_e32 v99, 1.0, v99
	v_add_f32_e32 v90, 1.0, v90
	v_exp_f32_e32 v83, v83
	v_exp_f32_e32 v50, v50
	v_mul_f32_e32 v51, 0xbfb8aa3b, v51
	v_add_f32_e32 v34, v34, v58
	v_mul_f32_e32 v127, v114, v115
	v_add_f32_e32 v115, v116, v60
	v_mul_f32_e32 v106, v110, v106
	v_add_f32_e32 v110, v111, v79
	v_rcp_f32_e32 v99, v99
	v_rcp_f32_e32 v90, v90
	v_add_f32_e32 v91, 1.0, v91
	v_exp_f32_e32 v51, v51
	v_mul_f32_e32 v34, 0xbfb8aa3b, v34
	v_add_f32_e32 v35, v35, v59
	v_mul_f32_e32 v115, 0xbfb8aa3b, v115
	v_mul_f32_e32 v107, v110, v107
	v_add_f32_e32 v110, v112, v80
	v_rcp_f32_e32 v91, v91
	v_add_f32_e32 v92, 1.0, v92
	v_exp_f32_e32 v34, v34
	v_mul_f32_e32 v35, 0xbfb8aa3b, v35
	v_add_f32_e32 v18, v18, v58
	v_add_f32_e32 v131, 1.0, v131
	v_exp_f32_e32 v115, v115
	v_mul_f32_e32 v108, v110, v108
	v_add_f32_e32 v110, v113, v81
	v_add_f32_e32 v102, v102, v66
	v_rcp_f32_e32 v92, v92
	v_add_f32_e32 v93, 1.0, v93
	v_add_f32_e32 v82, 1.0, v82
	v_exp_f32_e32 v35, v35
	v_mul_f32_e32 v18, 0xbfb8aa3b, v18
	v_add_f32_e32 v19, v19, v59
	v_rcp_f32_e32 v131, v131
	v_mul_f32_e32 v109, v110, v109
	v_mul_f32_e32 v110, v102, v98
	v_add_f32_e32 v98, v103, v67
	v_add_f32_e32 v94, v94, v78
	v_rcp_f32_e32 v93, v93
	v_rcp_f32_e32 v82, v82
	v_add_f32_e32 v83, 1.0, v83
	v_add_f32_e32 v50, 1.0, v50
	v_exp_f32_e32 v18, v18
	v_mul_f32_e32 v19, 0xbfb8aa3b, v19
	v_add_f32_e32 v2, v2, v58
	v_mul_f32_e32 v111, v98, v99
	v_add_f32_e32 v99, v100, v60
	v_mul_f32_e32 v90, v94, v90
	v_add_f32_e32 v94, v95, v79
	v_rcp_f32_e32 v83, v83
	v_rcp_f32_e32 v50, v50
	v_add_f32_e32 v51, 1.0, v51
	v_exp_f32_e32 v19, v19
	v_mul_f32_e32 v2, 0xbfb8aa3b, v2
	v_add_f32_e32 v3, v3, v59
	v_add_f32_e32 v134, v134, v74
	v_mul_f32_e32 v99, 0xbfb8aa3b, v99
	v_mul_f32_e32 v91, v94, v91
	v_add_f32_e32 v94, v96, v80
	v_rcp_f32_e32 v51, v51
	v_add_f32_e32 v34, 1.0, v34
	v_exp_f32_e32 v2, v2
	v_mul_f32_e32 v3, 0xbfb8aa3b, v3
	v_mul_f32_e32 v134, 0xbfb8aa3b, v134
	v_add_f32_e32 v135, v135, v75
	v_add_f32_e32 v130, v140, v68
	v_add_f32_e32 v115, 1.0, v115
	v_exp_f32_e32 v99, v99
	v_mul_f32_e32 v92, v94, v92
	v_add_f32_e32 v94, v97, v81
	v_add_f32_e32 v86, v86, v66
	v_rcp_f32_e32 v34, v34
	v_add_f32_e32 v35, 1.0, v35
	v_exp_f32_e32 v3, v3
	v_exp_f32_e32 v134, v134
	v_mul_f32_e32 v135, 0xbfb8aa3b, v135
	v_add_f32_e32 v136, v136, v76
	v_mul_f32_e32 v140, v130, v131
	v_add_f32_e32 v131, v133, v61
	v_rcp_f32_e32 v115, v115
	v_mul_f32_e32 v93, v94, v93
	v_mul_f32_e32 v94, v86, v82
	v_add_f32_e32 v82, v87, v67
	v_add_f32_e32 v54, v54, v66
	v_rcp_f32_e32 v35, v35
	v_add_f32_e32 v18, 1.0, v18
	v_exp_f32_e32 v135, v135
	v_mul_f32_e32 v136, 0xbfb8aa3b, v136
	v_add_f32_e32 v137, v137, v77
	v_mul_f32_e32 v131, 0xbfb8aa3b, v131
	v_mul_f32_e32 v95, v82, v83
	v_add_f32_e32 v83, v84, v60
	v_mul_f32_e32 v54, v54, v50
	v_add_f32_e32 v50, v55, v67
	v_rcp_f32_e32 v18, v18
	v_add_f32_e32 v19, 1.0, v19
	v_exp_f32_e32 v136, v136
	v_mul_f32_e32 v137, 0xbfb8aa3b, v137
	v_exp_f32_e32 v131, v131
	v_mul_f32_e32 v83, 0xbfb8aa3b, v83
	v_mul_f32_e32 v55, v50, v51
	v_add_f32_e32 v51, v52, v60
	v_add_f32_e32 v38, v38, v66
	v_rcp_f32_e32 v19, v19
	v_add_f32_e32 v2, 1.0, v2
	v_exp_f32_e32 v137, v137
	v_add_f32_e32 v114, v120, v68
	v_add_f32_e32 v99, 1.0, v99
	v_exp_f32_e32 v83, v83
	v_mul_f32_e32 v51, 0xbfb8aa3b, v51
	v_mul_f32_e32 v38, v38, v34
	v_add_f32_e32 v34, v39, v67
	v_rcp_f32_e32 v2, v2
	v_add_f32_e32 v3, 1.0, v3
	v_add_f32_e32 v134, 1.0, v134
	v_mul_f32_e32 v120, v114, v115
	v_add_f32_e32 v115, v117, v61
	v_rcp_f32_e32 v99, v99
	v_exp_f32_e32 v51, v51
	v_mul_f32_e32 v39, v34, v35
	v_add_f32_e32 v35, v36, v60
	v_add_f32_e32 v22, v22, v66
	v_rcp_f32_e32 v3, v3
	v_rcp_f32_e32 v134, v134
	v_add_f32_e32 v135, 1.0, v135
	v_mul_f32_e32 v115, 0xbfb8aa3b, v115
	v_mul_f32_e32 v35, 0xbfb8aa3b, v35
	v_mul_f32_e32 v22, v22, v18
	v_add_f32_e32 v18, v23, v67
	v_rcp_f32_e32 v135, v135
	v_add_f32_e32 v136, 1.0, v136
	v_add_f32_e32 v131, 1.0, v131
	v_exp_f32_e32 v115, v115
	v_exp_f32_e32 v35, v35
	v_mul_f32_e32 v23, v18, v19
	v_add_f32_e32 v19, v20, v60
	v_add_f32_e32 v6, v6, v66
	v_rcp_f32_e32 v136, v136
	v_add_f32_e32 v137, 1.0, v137
	v_rcp_f32_e32 v131, v131
	v_add_f32_e32 v98, v104, v68
	v_add_f32_e32 v83, 1.0, v83
	v_mul_f32_e32 v19, 0xbfb8aa3b, v19
	v_mul_f32_e32 v6, v6, v2
	v_add_f32_e32 v2, v7, v67
	v_add_f32_e32 v142, v142, v78
	v_rcp_f32_e32 v137, v137
	v_mul_f32_e32 v104, v98, v99
	v_add_f32_e32 v99, v101, v61
	v_rcp_f32_e32 v83, v83
	v_add_f32_e32 v51, 1.0, v51
	v_exp_f32_e32 v19, v19
	v_mul_f32_e32 v7, v2, v3
	v_add_f32_e32 v3, v4, v60
	v_mul_f32_e32 v134, v142, v134
	v_add_f32_e32 v142, v143, v79
	v_mul_f32_e32 v99, 0xbfb8aa3b, v99
	v_rcp_f32_e32 v51, v51
	v_mul_f32_e32 v3, 0xbfb8aa3b, v3
	v_mul_f32_e32 v135, v142, v135
	v_add_f32_e32 v142, v144, v80
	v_add_f32_e32 v130, v141, v69
	v_add_f32_e32 v115, 1.0, v115
	v_exp_f32_e32 v99, v99
	v_add_f32_e32 v62, v62, v74
	v_add_f32_e32 v35, 1.0, v35
	v_exp_f32_e32 v3, v3
	v_mul_f32_e32 v136, v142, v136
	v_add_f32_e32 v142, v145, v81
	v_mul_f32_e32 v141, v130, v131
	v_lshl_add_u64 v[130:131], v[172:173], 0, v[182:183]
	v_cvt_pk_bf16_f32 v132, v134, v135
	v_rcp_f32_e32 v115, v115
	v_add_f32_e32 v82, v88, v68
	v_mul_f32_e32 v62, 0xbfb8aa3b, v62
	v_add_f32_e32 v63, v63, v75
	v_rcp_f32_e32 v35, v35
	v_mul_f32_e32 v137, v142, v137
	v_cvt_pk_bf16_f32 v133, v136, v137
	v_cvt_pk_bf16_f32 v134, v138, v139
	v_cvt_pk_bf16_f32 v135, v140, v141
	global_store_dwordx4 v[130:131], v[132:135], off
	v_mul_f32_e32 v88, v82, v83
	v_add_f32_e32 v83, v85, v61
	v_or_b32_e32 v132, 16, v174
	v_exp_f32_e32 v62, v62
	v_mul_f32_e32 v63, 0xbfb8aa3b, v63
	v_add_f32_e32 v64, v64, v76
	v_add_f32_e32 v50, v56, v68
	v_add_f32_e32 v42, v42, v74
	v_add_f32_e32 v19, 1.0, v19
	v_ashrrev_i32_e32 v133, 31, v132
	v_mul_f32_e32 v83, 0xbfb8aa3b, v83
	v_exp_f32_e32 v63, v63
	v_mul_f32_e32 v64, 0xbfb8aa3b, v64
	v_add_f32_e32 v65, v65, v77
	v_mul_f32_e32 v56, v50, v51
	v_add_f32_e32 v51, v53, v61
	v_mul_f32_e32 v42, 0xbfb8aa3b, v42
	v_add_f32_e32 v43, v43, v75
	v_rcp_f32_e32 v19, v19
	v_lshlrev_b64 v[132:133], 11, v[132:133]
	v_add_f32_e32 v114, v121, v69
	v_add_f32_e32 v99, 1.0, v99
	v_exp_f32_e32 v83, v83
	v_exp_f32_e32 v64, v64
	v_mul_f32_e32 v65, 0xbfb8aa3b, v65
	v_mul_f32_e32 v51, 0xbfb8aa3b, v51
	v_exp_f32_e32 v42, v42
	v_mul_f32_e32 v43, 0xbfb8aa3b, v43
	v_add_f32_e32 v44, v44, v76
	v_add_f32_e32 v34, v40, v68
	v_add_f32_e32 v26, v26, v74
	v_add_f32_e32 v3, 1.0, v3
	v_mul_f32_e32 v117, v114, v115
	v_lshl_add_u64 v[118:119], v[172:173], 0, v[132:133]
	v_cvt_pk_bf16_f32 v114, v122, v123
	v_rcp_f32_e32 v99, v99
	v_exp_f32_e32 v65, v65
	v_exp_f32_e32 v51, v51
	v_exp_f32_e32 v43, v43
	v_mul_f32_e32 v44, 0xbfb8aa3b, v44
	v_add_f32_e32 v45, v45, v77
	v_mul_f32_e32 v40, v34, v35
	v_add_f32_e32 v35, v37, v61
	v_mul_f32_e32 v26, 0xbfb8aa3b, v26
	v_add_f32_e32 v27, v27, v75
	v_rcp_f32_e32 v3, v3
	v_cvt_pk_bf16_f32 v115, v124, v125
	v_cvt_pk_bf16_f32 v116, v126, v127
	v_cvt_pk_bf16_f32 v117, v120, v117
	global_store_dwordx4 v[118:119], v[114:117], off
	v_add_f32_e32 v62, 1.0, v62
	v_exp_f32_e32 v44, v44
	v_or_b32_e32 v114, 32, v174
	v_mul_f32_e32 v45, 0xbfb8aa3b, v45
	v_mul_f32_e32 v35, 0xbfb8aa3b, v35
	v_exp_f32_e32 v26, v26
	v_mul_f32_e32 v27, 0xbfb8aa3b, v27
	v_add_f32_e32 v28, v28, v76
	v_add_f32_e32 v18, v24, v68
	v_add_f32_e32 v10, v10, v74
	v_ashrrev_i32_e32 v115, 31, v114
	v_rcp_f32_e32 v62, v62
	v_add_f32_e32 v63, 1.0, v63
	v_exp_f32_e32 v45, v45
	v_exp_f32_e32 v35, v35
	v_exp_f32_e32 v27, v27
	v_mul_f32_e32 v28, 0xbfb8aa3b, v28
	v_add_f32_e32 v29, v29, v77
	v_mul_f32_e32 v24, v18, v19
	v_add_f32_e32 v19, v21, v61
	v_mul_f32_e32 v10, 0xbfb8aa3b, v10
	v_add_f32_e32 v11, v11, v75
	v_lshlrev_b64 v[114:115], 11, v[114:115]
	v_add_f32_e32 v98, v105, v69
	v_add_f32_e32 v83, 1.0, v83
	v_rcp_f32_e32 v63, v63
	v_add_f32_e32 v64, 1.0, v64
	v_add_f32_e32 v42, 1.0, v42
	v_exp_f32_e32 v28, v28
	v_mul_f32_e32 v29, 0xbfb8aa3b, v29
	v_mul_f32_e32 v19, 0xbfb8aa3b, v19
	v_exp_f32_e32 v10, v10
	v_mul_f32_e32 v11, 0xbfb8aa3b, v11
	v_add_f32_e32 v12, v12, v76
	v_add_f32_e32 v2, v8, v68
	v_mul_f32_e32 v101, v98, v99
	v_lshl_add_u64 v[102:103], v[172:173], 0, v[114:115]
	v_cvt_pk_bf16_f32 v98, v106, v107
	v_rcp_f32_e32 v83, v83
	v_rcp_f32_e32 v64, v64
	v_add_f32_e32 v65, 1.0, v65
	v_add_f32_e32 v51, 1.0, v51
	v_rcp_f32_e32 v42, v42
	v_add_f32_e32 v43, 1.0, v43
	v_exp_f32_e32 v29, v29
	v_exp_f32_e32 v19, v19
	v_exp_f32_e32 v11, v11
	v_mul_f32_e32 v12, 0xbfb8aa3b, v12
	v_add_f32_e32 v13, v13, v77
	v_mul_f32_e32 v8, v2, v3
	v_add_f32_e32 v3, v5, v61
	v_cvt_pk_bf16_f32 v99, v108, v109
	v_cvt_pk_bf16_f32 v100, v110, v111
	v_cvt_pk_bf16_f32 v101, v104, v101
	global_store_dwordx4 v[102:103], v[98:101], off
	v_add_f32_e32 v70, v70, v78
	v_rcp_f32_e32 v65, v65
	v_or_b32_e32 v98, 48, v174
	v_rcp_f32_e32 v51, v51
	v_rcp_f32_e32 v43, v43
	v_add_f32_e32 v44, 1.0, v44
	v_add_f32_e32 v26, 1.0, v26
	v_exp_f32_e32 v12, v12
	v_mul_f32_e32 v13, 0xbfb8aa3b, v13
	v_mul_f32_e32 v3, 0xbfb8aa3b, v3
	v_ashrrev_i32_e32 v99, 31, v98
	v_mul_f32_e32 v62, v70, v62
	v_add_f32_e32 v70, v71, v79
	v_rcp_f32_e32 v44, v44
	v_add_f32_e32 v45, 1.0, v45
	v_add_f32_e32 v35, 1.0, v35
	v_rcp_f32_e32 v26, v26
	v_add_f32_e32 v27, 1.0, v27
	v_exp_f32_e32 v13, v13
	v_exp_f32_e32 v3, v3
	v_lshlrev_b64 v[98:99], 11, v[98:99]
	v_add_f32_e32 v82, v89, v69
	v_mul_f32_e32 v63, v70, v63
	v_add_f32_e32 v70, v72, v80
	v_add_f32_e32 v46, v46, v78
	v_rcp_f32_e32 v45, v45
	v_rcp_f32_e32 v35, v35
	v_rcp_f32_e32 v27, v27
	v_add_f32_e32 v28, 1.0, v28
	v_add_f32_e32 v10, 1.0, v10
	v_mul_f32_e32 v85, v82, v83
	v_lshl_add_u64 v[86:87], v[172:173], 0, v[98:99]
	v_mul_f32_e32 v64, v70, v64
	v_add_f32_e32 v70, v73, v81
	v_add_f32_e32 v50, v57, v69
	v_mul_f32_e32 v42, v46, v42
	v_add_f32_e32 v46, v47, v79
	v_rcp_f32_e32 v28, v28
	v_add_f32_e32 v29, 1.0, v29
	v_add_f32_e32 v19, 1.0, v19
	v_rcp_f32_e32 v10, v10
	v_add_f32_e32 v11, 1.0, v11
	v_cvt_pk_bf16_f32 v82, v90, v91
	v_cvt_pk_bf16_f32 v83, v92, v93
	v_cvt_pk_bf16_f32 v84, v94, v95
	v_cvt_pk_bf16_f32 v85, v88, v85
	global_store_dwordx4 v[86:87], v[82:85], off
	v_mul_f32_e32 v65, v70, v65
	v_mul_f32_e32 v53, v50, v51
	v_cvt_pk_bf16_f32 v50, v62, v63
	v_cvt_pk_bf16_f32 v51, v64, v65
	v_cvt_pk_bf16_f32 v52, v54, v55
	v_add_co_u32_e32 v54, vcc, s67, v130
	v_mul_f32_e32 v43, v46, v43
	v_add_f32_e32 v46, v48, v80
	v_add_f32_e32 v30, v30, v78
	v_rcp_f32_e32 v29, v29
	v_rcp_f32_e32 v19, v19
	v_rcp_f32_e32 v11, v11
	v_add_f32_e32 v12, 1.0, v12
	v_addc_co_u32_e32 v55, vcc, 0, v131, vcc
	v_mul_f32_e32 v44, v46, v44
	v_add_f32_e32 v46, v49, v81
	v_add_f32_e32 v34, v41, v69
	v_mul_f32_e32 v26, v30, v26
	v_add_f32_e32 v30, v31, v79
	v_rcp_f32_e32 v12, v12
	v_add_f32_e32 v13, 1.0, v13
	v_add_f32_e32 v3, 1.0, v3
	v_cvt_pk_bf16_f32 v53, v56, v53
	global_store_dwordx4 v[54:55], v[50:53], off
	v_mul_f32_e32 v45, v46, v45
	v_mul_f32_e32 v37, v34, v35
	v_cvt_pk_bf16_f32 v34, v42, v43
	v_cvt_pk_bf16_f32 v35, v44, v45
	v_cvt_pk_bf16_f32 v36, v38, v39
	v_add_co_u32_e32 v38, vcc, s68, v130
	v_mul_f32_e32 v27, v30, v27
	v_add_f32_e32 v30, v32, v80
	v_add_f32_e32 v14, v14, v78
	v_rcp_f32_e32 v13, v13
	v_rcp_f32_e32 v3, v3
	v_addc_co_u32_e32 v39, vcc, 0, v131, vcc
	v_mul_f32_e32 v28, v30, v28
	v_add_f32_e32 v30, v33, v81
	v_add_f32_e32 v18, v25, v69
	v_mul_f32_e32 v10, v14, v10
	v_add_f32_e32 v14, v15, v79
	v_cvt_pk_bf16_f32 v37, v40, v37
	global_store_dwordx4 v[38:39], v[34:37], off
	v_mul_f32_e32 v29, v30, v29
	v_mul_f32_e32 v21, v18, v19
	v_cvt_pk_bf16_f32 v18, v26, v27
	v_cvt_pk_bf16_f32 v19, v28, v29
	v_cvt_pk_bf16_f32 v20, v22, v23
	v_add_co_u32_e32 v22, vcc, s2, v130
	v_mul_f32_e32 v11, v14, v11
	v_add_f32_e32 v14, v16, v80
	v_addc_co_u32_e32 v23, vcc, 0, v131, vcc
	v_mul_f32_e32 v12, v14, v12
	v_add_f32_e32 v14, v17, v81
	v_add_f32_e32 v2, v9, v69
	v_cvt_pk_bf16_f32 v21, v24, v21
	global_store_dwordx4 v[22:23], v[18:21], off
	v_mul_f32_e32 v13, v14, v13
	v_mul_f32_e32 v5, v2, v3
	v_cvt_pk_bf16_f32 v2, v10, v11
	v_cvt_pk_bf16_f32 v3, v12, v13
	v_cvt_pk_bf16_f32 v4, v6, v7
	v_add_co_u32_e32 v6, vcc, 0x58000, v130
	s_mov_b32 s2, s48
	s_nop 0
	v_addc_co_u32_e32 v7, vcc, 0, v131, vcc
	s_and_b64 vcc, exec, s[38:39]
	v_cvt_pk_bf16_f32 v5, v8, v5
	global_store_dwordx4 v[6:7], v[2:5], off
	s_cbranch_vccz .LBB0_88
	s_waitcnt vmcnt(8)
	s_cmpk_gt_u32 s35, 0xff
	s_cbranch_scc1 .LBB0_99
	s_barrier

.Lkprio_3:
.LBB0_260:
	s_add_u32 s22, s0, 0xfffc0080
	s_addc_u32 s23, s1, -1
	s_add_i32 s60, 0, 0x10000
	v_add_u32_e32 v142, s60, v178
	ds_read_b128 v[130:133], v142
	ds_read_b128 v[134:137], v142 offset:1024
	ds_read_b128 v[138:141], v142 offset:2048
	ds_read_b128 v[142:145], v142 offset:3072
	s_cmp_eq_u32 s59, 12
	s_cselect_b32 s47, s35, s23
	s_cselect_b32 s46, s55, s22
	s_cselect_b32 s23, s31, s58
	s_cselect_b32 s22, s56, s57
	v_lshl_add_u64 v[186:187], s[0:1], 0, v[168:169]
	s_add_i32 m0, s27, 0xc000
	ds_read_b128 v[172:175], v180
	ds_read_b128 v[182:185], v180 offset:1024
	ds_read_b128 v[206:209], v180 offset:2048
	ds_read_b128 v[210:213], v180 offset:3072
	ds_read_b128 v[214:217], v180 offset:4096
	ds_read_b128 v[218:221], v180 offset:5120
	ds_read_b128 v[222:225], v180 offset:6144
	ds_read_b128 v[226:229], v180 offset:7168
	global_load_lds_dwordx4 v[186:187], off
	s_add_i32 m0, s27, 0xe000
	v_lshl_add_u64 v[186:187], s[0:1], 0, v[170:171]
	global_load_lds_dwordx4 v[186:187], off
	s_waitcnt lgkmcnt(8)
	s_barrier
	s_waitcnt lgkmcnt(0)
	v_mfma_f32_16x16x32_bf16 v[126:129], v[130:133], v[172:175], v[126:129]
	v_mfma_f32_16x16x32_bf16 v[122:125], v[138:141], v[172:175], v[122:125]
	v_mfma_f32_16x16x32_bf16 v[110:113], v[130:133], v[206:209], v[110:113]
	v_mfma_f32_16x16x32_bf16 v[106:109], v[138:141], v[206:209], v[106:109]
	v_mfma_f32_16x16x32_bf16 v[94:97], v[130:133], v[214:217], v[94:97]
	v_mfma_f32_16x16x32_bf16 v[90:93], v[138:141], v[214:217], v[90:93]
	v_mfma_f32_16x16x32_bf16 v[78:81], v[130:133], v[222:225], v[78:81]
	v_mfma_f32_16x16x32_bf16 v[74:77], v[138:141], v[222:225], v[74:77]
	v_mfma_f32_16x16x32_bf16 v[126:129], v[134:137], v[182:185], v[126:129]
	v_mfma_f32_16x16x32_bf16 v[122:125], v[142:145], v[182:185], v[122:125]
	v_mfma_f32_16x16x32_bf16 v[110:113], v[134:137], v[210:213], v[110:113]
	v_mfma_f32_16x16x32_bf16 v[106:109], v[142:145], v[210:213], v[106:109]
	v_mfma_f32_16x16x32_bf16 v[94:97], v[134:137], v[218:221], v[94:97]
	v_mfma_f32_16x16x32_bf16 v[90:93], v[142:145], v[218:221], v[90:93]
	v_mfma_f32_16x16x32_bf16 v[78:81], v[134:137], v[226:229], v[78:81]
	v_mfma_f32_16x16x32_bf16 v[74:77], v[142:145], v[226:229], v[74:77]
	s_barrier
	s_add_i32 s62, 0, 0x14000
	s_add_i32 s60, s60, s25
	v_add_u32_e32 v181, s62, v178
	v_lshl_add_u64 v[186:187], s[22:23], 0, v[0:1]
	s_mov_b32 m0, s60
	ds_read_b128 v[230:233], v181
	ds_read_b128 v[234:237], v181 offset:1024
	ds_read_b128 v[238:241], v181 offset:2048
	ds_read_b128 v[242:245], v181 offset:3072
	global_load_lds_dwordx4 v[186:187], off
	s_add_i32 m0, s60, 0x2000
	v_lshl_add_u64 v[246:247], s[22:23], 0, v[162:163]
	global_load_lds_dwordx4 v[246:247], off
	s_barrier
	s_waitcnt lgkmcnt(0)
	v_mfma_f32_16x16x32_bf16 v[118:121], v[230:233], v[172:175], v[118:121]
	v_mfma_f32_16x16x32_bf16 v[114:117], v[238:241], v[172:175], v[114:117]
	v_mfma_f32_16x16x32_bf16 v[102:105], v[230:233], v[206:209], v[102:105]
	v_mfma_f32_16x16x32_bf16 v[98:101], v[238:241], v[206:209], v[98:101]
	v_mfma_f32_16x16x32_bf16 v[86:89], v[230:233], v[214:217], v[86:89]
	v_mfma_f32_16x16x32_bf16 v[82:85], v[238:241], v[214:217], v[82:85]
	v_mfma_f32_16x16x32_bf16 v[70:73], v[230:233], v[222:225], v[70:73]
	v_mfma_f32_16x16x32_bf16 v[66:69], v[238:241], v[222:225], v[66:69]
	v_mfma_f32_16x16x32_bf16 v[118:121], v[234:237], v[182:185], v[118:121]
	v_mfma_f32_16x16x32_bf16 v[114:117], v[242:245], v[182:185], v[114:117]
	v_mfma_f32_16x16x32_bf16 v[102:105], v[234:237], v[210:213], v[102:105]
	v_mfma_f32_16x16x32_bf16 v[98:101], v[242:245], v[210:213], v[98:101]
	v_mfma_f32_16x16x32_bf16 v[86:89], v[234:237], v[218:221], v[86:89]
	v_mfma_f32_16x16x32_bf16 v[82:85], v[242:245], v[218:221], v[82:85]
	v_mfma_f32_16x16x32_bf16 v[70:73], v[234:237], v[226:229], v[70:73]
	v_mfma_f32_16x16x32_bf16 v[66:69], v[242:245], v[226:229], v[66:69]
	s_barrier
	s_mov_b32 m0, s27
	v_lshl_add_u64 v[248:249], s[46:47], 0, v[166:167]
	ds_read_b128 v[172:175], v180 offset:16384
	ds_read_b128 v[182:185], v180 offset:17408
	ds_read_b128 v[206:209], v180 offset:18432
	ds_read_b128 v[210:213], v180 offset:19456
	ds_read_b128 v[214:217], v180 offset:20480
	ds_read_b128 v[218:221], v180 offset:21504
	ds_read_b128 v[222:225], v180 offset:22528
	ds_read_b128 v[226:229], v180 offset:23552
	global_load_lds_dwordx4 v[248:249], off
	s_mov_b32 m0, s45
	v_lshl_add_u64 v[250:251], s[46:47], 0, v[164:165]
	global_load_lds_dwordx4 v[250:251], off
	s_barrier
	s_waitcnt lgkmcnt(0)
	v_mfma_f32_16x16x32_bf16 v[62:65], v[130:133], v[172:175], v[62:65]
	v_mfma_f32_16x16x32_bf16 v[58:61], v[138:141], v[172:175], v[58:61]
	v_mfma_f32_16x16x32_bf16 v[50:53], v[130:133], v[206:209], v[50:53]
	v_mfma_f32_16x16x32_bf16 v[42:45], v[138:141], v[206:209], v[42:45]
	v_mfma_f32_16x16x32_bf16 v[34:37], v[130:133], v[214:217], v[34:37]
	v_mfma_f32_16x16x32_bf16 v[26:29], v[138:141], v[214:217], v[26:29]
	v_mfma_f32_16x16x32_bf16 v[18:21], v[130:133], v[222:225], v[18:21]
	v_mfma_f32_16x16x32_bf16 v[10:13], v[138:141], v[222:225], v[10:13]
	v_mfma_f32_16x16x32_bf16 v[62:65], v[134:137], v[182:185], v[62:65]
	v_mfma_f32_16x16x32_bf16 v[58:61], v[142:145], v[182:185], v[58:61]
	v_mfma_f32_16x16x32_bf16 v[50:53], v[134:137], v[210:213], v[50:53]
	v_mfma_f32_16x16x32_bf16 v[42:45], v[142:145], v[210:213], v[42:45]
	v_mfma_f32_16x16x32_bf16 v[34:37], v[134:137], v[218:221], v[34:37]
	v_mfma_f32_16x16x32_bf16 v[26:29], v[142:145], v[218:221], v[26:29]
	v_mfma_f32_16x16x32_bf16 v[18:21], v[134:137], v[226:229], v[18:21]
	v_mfma_f32_16x16x32_bf16 v[10:13], v[142:145], v[226:229], v[10:13]
	s_barrier
	s_add_u32 s60, s22, 0x40000
	s_addc_u32 s61, s23, 0
	s_add_i32 s62, s62, s25
	s_mov_b32 m0, s62
	v_lshl_add_u64 v[130:131], s[60:61], 0, v[0:1]
	global_load_lds_dwordx4 v[130:131], off
	s_add_i32 m0, s62, 0x2000
	v_lshl_add_u64 v[130:131], s[60:61], 0, v[162:163]
	global_load_lds_dwordx4 v[130:131], off
	s_waitcnt vmcnt(6)
	s_barrier
	v_mfma_f32_16x16x32_bf16 v[54:57], v[230:233], v[172:175], v[54:57]
	v_mfma_f32_16x16x32_bf16 v[46:49], v[238:241], v[172:175], v[46:49]
	v_mfma_f32_16x16x32_bf16 v[38:41], v[230:233], v[206:209], v[38:41]
	v_mfma_f32_16x16x32_bf16 v[30:33], v[238:241], v[206:209], v[30:33]
	v_mfma_f32_16x16x32_bf16 v[22:25], v[230:233], v[214:217], v[22:25]
	v_mfma_f32_16x16x32_bf16 v[14:17], v[238:241], v[214:217], v[14:17]
	v_mfma_f32_16x16x32_bf16 v[6:9], v[230:233], v[222:225], v[6:9]
	v_mfma_f32_16x16x32_bf16 v[2:5], v[238:241], v[222:225], v[2:5]
	v_mfma_f32_16x16x32_bf16 v[54:57], v[234:237], v[182:185], v[54:57]
	v_mfma_f32_16x16x32_bf16 v[46:49], v[242:245], v[182:185], v[46:49]
	v_mfma_f32_16x16x32_bf16 v[38:41], v[234:237], v[210:213], v[38:41]
	v_mfma_f32_16x16x32_bf16 v[30:33], v[242:245], v[210:213], v[30:33]
	v_mfma_f32_16x16x32_bf16 v[22:25], v[234:237], v[218:221], v[22:25]
	v_mfma_f32_16x16x32_bf16 v[14:17], v[242:245], v[218:221], v[14:17]
	v_mfma_f32_16x16x32_bf16 v[6:9], v[234:237], v[226:229], v[6:9]
	v_mfma_f32_16x16x32_bf16 v[2:5], v[242:245], v[226:229], v[2:5]
	s_barrier
	s_add_i32 s60, 0, 0x18000
	v_add_u32_e32 v142, s60, v178
	ds_read_b128 v[130:133], v142
	ds_read_b128 v[134:137], v142 offset:1024
	ds_read_b128 v[138:141], v142 offset:2048
	ds_read_b128 v[142:145], v142 offset:3072
	s_add_u32 s46, s46, 0x40000
	s_addc_u32 s47, s47, 0
	s_mov_b32 m0, s48
	v_lshl_add_u64 v[230:231], s[46:47], 0, v[166:167]
	ds_read_b128 v[172:175], v180 offset:32768
	ds_read_b128 v[182:185], v180 offset:33792
	ds_read_b128 v[206:209], v180 offset:34816
	ds_read_b128 v[210:213], v180 offset:35840
	ds_read_b128 v[214:217], v180 offset:36864
	ds_read_b128 v[218:221], v180 offset:37888
	ds_read_b128 v[222:225], v180 offset:38912
	ds_read_b128 v[226:229], v180 offset:39936
	global_load_lds_dwordx4 v[230:231], off
	s_mov_b32 m0, s49
	v_lshl_add_u64 v[230:231], s[46:47], 0, v[164:165]
	global_load_lds_dwordx4 v[230:231], off
	s_waitcnt lgkmcnt(8)
	s_barrier
	s_waitcnt lgkmcnt(0)
	v_mfma_f32_16x16x32_bf16 v[126:129], v[130:133], v[172:175], v[126:129]
	v_mfma_f32_16x16x32_bf16 v[122:125], v[138:141], v[172:175], v[122:125]
	v_mfma_f32_16x16x32_bf16 v[110:113], v[130:133], v[206:209], v[110:113]
	v_mfma_f32_16x16x32_bf16 v[106:109], v[138:141], v[206:209], v[106:109]
	v_mfma_f32_16x16x32_bf16 v[94:97], v[130:133], v[214:217], v[94:97]
	v_mfma_f32_16x16x32_bf16 v[90:93], v[138:141], v[214:217], v[90:93]
	v_mfma_f32_16x16x32_bf16 v[78:81], v[130:133], v[222:225], v[78:81]
	v_mfma_f32_16x16x32_bf16 v[74:77], v[138:141], v[222:225], v[74:77]
	v_mfma_f32_16x16x32_bf16 v[126:129], v[134:137], v[182:185], v[126:129]
	v_mfma_f32_16x16x32_bf16 v[122:125], v[142:145], v[182:185], v[122:125]
	v_mfma_f32_16x16x32_bf16 v[110:113], v[134:137], v[210:213], v[110:113]
	v_mfma_f32_16x16x32_bf16 v[106:109], v[142:145], v[210:213], v[106:109]
	v_mfma_f32_16x16x32_bf16 v[94:97], v[134:137], v[218:221], v[94:97]
	v_mfma_f32_16x16x32_bf16 v[90:93], v[142:145], v[218:221], v[90:93]
	v_mfma_f32_16x16x32_bf16 v[78:81], v[134:137], v[226:229], v[78:81]
	v_mfma_f32_16x16x32_bf16 v[74:77], v[142:145], v[226:229], v[74:77]
	s_barrier
	s_add_i32 s46, 0, 0x1c000
	s_add_i32 s47, s60, s25
	v_add_u32_e32 v181, s46, v178
	v_lshl_add_u64 v[186:187], v[186:187], 0, s[94:95]
	s_mov_b32 m0, s47
	ds_read_b128 v[230:233], v181
	ds_read_b128 v[234:237], v181 offset:1024
	ds_read_b128 v[238:241], v181 offset:2048
	ds_read_b128 v[242:245], v181 offset:3072
	global_load_lds_dwordx4 v[186:187], off
	s_add_i32 m0, s47, 0x2000
	v_lshl_add_u64 v[186:187], v[246:247], 0, s[94:95]
	global_load_lds_dwordx4 v[186:187], off
	s_barrier
	s_waitcnt lgkmcnt(0)
	v_mfma_f32_16x16x32_bf16 v[118:121], v[230:233], v[172:175], v[118:121]
	v_mfma_f32_16x16x32_bf16 v[114:117], v[238:241], v[172:175], v[114:117]
	v_mfma_f32_16x16x32_bf16 v[102:105], v[230:233], v[206:209], v[102:105]
	v_mfma_f32_16x16x32_bf16 v[98:101], v[238:241], v[206:209], v[98:101]
	v_mfma_f32_16x16x32_bf16 v[86:89], v[230:233], v[214:217], v[86:89]
	v_mfma_f32_16x16x32_bf16 v[82:85], v[238:241], v[214:217], v[82:85]
	v_mfma_f32_16x16x32_bf16 v[70:73], v[230:233], v[222:225], v[70:73]
	v_mfma_f32_16x16x32_bf16 v[66:69], v[238:241], v[222:225], v[66:69]
	v_mfma_f32_16x16x32_bf16 v[118:121], v[234:237], v[182:185], v[118:121]
	v_mfma_f32_16x16x32_bf16 v[114:117], v[242:245], v[182:185], v[114:117]
	v_mfma_f32_16x16x32_bf16 v[102:105], v[234:237], v[210:213], v[102:105]
	v_mfma_f32_16x16x32_bf16 v[98:101], v[242:245], v[210:213], v[98:101]
	v_mfma_f32_16x16x32_bf16 v[86:89], v[234:237], v[218:221], v[86:89]
	v_mfma_f32_16x16x32_bf16 v[82:85], v[242:245], v[218:221], v[82:85]
	v_mfma_f32_16x16x32_bf16 v[70:73], v[234:237], v[226:229], v[70:73]
	v_mfma_f32_16x16x32_bf16 v[66:69], v[242:245], v[226:229], v[66:69]
	s_barrier
	s_mov_b32 m0, s51
	v_lshl_add_u64 v[186:187], v[248:249], 0, s[94:95]
	ds_read_b128 v[172:175], v180 offset:49152
	ds_read_b128 v[182:185], v180 offset:50176
	ds_read_b128 v[206:209], v180 offset:51200
	ds_read_b128 v[210:213], v180 offset:52224
	ds_read_b128 v[214:217], v180 offset:53248
	ds_read_b128 v[218:221], v180 offset:54272
	ds_read_b128 v[222:225], v180 offset:55296
	ds_read_b128 v[226:229], v180 offset:56320
	global_load_lds_dwordx4 v[186:187], off
	s_mov_b32 m0, s52
	v_lshl_add_u64 v[186:187], v[250:251], 0, s[94:95]
	global_load_lds_dwordx4 v[186:187], off
	s_barrier
	s_waitcnt lgkmcnt(0)
	v_mfma_f32_16x16x32_bf16 v[62:65], v[130:133], v[172:175], v[62:65]
	v_mfma_f32_16x16x32_bf16 v[58:61], v[138:141], v[172:175], v[58:61]
	v_mfma_f32_16x16x32_bf16 v[50:53], v[130:133], v[206:209], v[50:53]
	v_mfma_f32_16x16x32_bf16 v[42:45], v[138:141], v[206:209], v[42:45]
	v_mfma_f32_16x16x32_bf16 v[34:37], v[130:133], v[214:217], v[34:37]
	v_mfma_f32_16x16x32_bf16 v[26:29], v[138:141], v[214:217], v[26:29]
	v_mfma_f32_16x16x32_bf16 v[18:21], v[130:133], v[222:225], v[18:21]
	v_mfma_f32_16x16x32_bf16 v[10:13], v[138:141], v[222:225], v[10:13]
	v_mfma_f32_16x16x32_bf16 v[62:65], v[134:137], v[182:185], v[62:65]
	v_mfma_f32_16x16x32_bf16 v[58:61], v[142:145], v[182:185], v[58:61]
	v_mfma_f32_16x16x32_bf16 v[50:53], v[134:137], v[210:213], v[50:53]
	v_mfma_f32_16x16x32_bf16 v[42:45], v[142:145], v[210:213], v[42:45]
	v_mfma_f32_16x16x32_bf16 v[34:37], v[134:137], v[218:221], v[34:37]
	v_mfma_f32_16x16x32_bf16 v[26:29], v[142:145], v[218:221], v[26:29]
	v_mfma_f32_16x16x32_bf16 v[18:21], v[134:137], v[226:229], v[18:21]
	v_mfma_f32_16x16x32_bf16 v[10:13], v[142:145], v[226:229], v[10:13]
	s_barrier
	s_add_u32 s22, s22, 0x40080
	s_addc_u32 s23, s23, 0
	s_add_i32 s46, s46, s25
	s_mov_b32 m0, s46
	v_lshl_add_u64 v[130:131], s[22:23], 0, v[0:1]
	global_load_lds_dwordx4 v[130:131], off
	s_add_i32 m0, s46, 0x2000
	v_lshl_add_u64 v[130:131], s[22:23], 0, v[162:163]
	global_load_lds_dwordx4 v[130:131], off
	s_waitcnt vmcnt(6)
	s_barrier
	v_mfma_f32_16x16x32_bf16 v[54:57], v[230:233], v[172:175], v[54:57]
	v_mfma_f32_16x16x32_bf16 v[46:49], v[238:241], v[172:175], v[46:49]
	v_mfma_f32_16x16x32_bf16 v[38:41], v[230:233], v[206:209], v[38:41]
	v_mfma_f32_16x16x32_bf16 v[30:33], v[238:241], v[206:209], v[30:33]
	v_mfma_f32_16x16x32_bf16 v[22:25], v[230:233], v[214:217], v[22:25]
	v_mfma_f32_16x16x32_bf16 v[14:17], v[238:241], v[214:217], v[14:17]
	v_mfma_f32_16x16x32_bf16 v[6:9], v[230:233], v[222:225], v[6:9]
	v_mfma_f32_16x16x32_bf16 v[2:5], v[238:241], v[222:225], v[2:5]
	v_mfma_f32_16x16x32_bf16 v[54:57], v[234:237], v[182:185], v[54:57]
	v_mfma_f32_16x16x32_bf16 v[46:49], v[242:245], v[182:185], v[46:49]
	v_mfma_f32_16x16x32_bf16 v[38:41], v[234:237], v[210:213], v[38:41]
	v_mfma_f32_16x16x32_bf16 v[30:33], v[242:245], v[210:213], v[30:33]
	v_mfma_f32_16x16x32_bf16 v[22:25], v[234:237], v[218:221], v[22:25]
	v_mfma_f32_16x16x32_bf16 v[14:17], v[242:245], v[218:221], v[14:17]
	v_mfma_f32_16x16x32_bf16 v[6:9], v[234:237], v[226:229], v[6:9]
	v_mfma_f32_16x16x32_bf16 v[2:5], v[242:245], v[226:229], v[2:5]
	s_barrier
	s_add_i32 s59, s59, 2
	s_add_u32 s0, s0, 0x100
	s_addc_u32 s1, s1, 0
	s_add_u32 s57, s57, 0x100
	s_addc_u32 s58, s58, 0
	s_cmp_gt_u32 s59, 13
	s_cbranch_scc0 .LBB0_260
	v_lshl_or_b32 v172, s54, 8, v179
	v_ashrrev_i32_e32 v173, 31, v172
	v_cndmask_b32_e64 v131, 0, 1, s[2:3]
	v_lshl_add_u64 v[174:175], v[172:173], 2, s[8:9]
	v_mov_b32_e32 v130, 0
	v_cmp_ne_u32_e64 s[0:1], 1, v131
	s_andn2_b64 vcc, exec, s[2:3]
	v_mov_b32_e32 v134, 0
	v_mov_b32_e32 v135, 0
	v_mov_b32_e32 v136, 0
	v_mov_b32_e32 v137, 0
	s_cbranch_vccnz .LBB0_263
	global_load_dwordx4 v[134:137], v[174:175], off

.Lkprio_2:
.LBB0_331:
	s_add_u32 s22, s24, 0x100
	s_addc_u32 s23, s25, 0
	s_add_i32 s52, 0, 0x10000
	v_add_u32_e32 v140, s52, v144
	ds_read_b128 v[164:167], v140
	ds_read_b128 v[168:171], v140 offset:1024
	ds_read_b128 v[172:175], v140 offset:2048
	ds_read_b128 v[176:179], v140 offset:3072
	s_cmp_eq_u32 s51, 40
	s_cselect_b32 s29, s3, s23
	s_cselect_b32 s28, s2, s22
	s_cselect_b32 s27, s1, s41
	s_cselect_b32 s26, s0, s40
	v_lshl_add_u64 v[140:141], s[24:25], 0, v[136:137]
	s_add_i32 m0, s35, 0xc000
	ds_read_b128 v[180:183], v162
	ds_read_b128 v[184:187], v162 offset:1024
	ds_read_b128 v[206:209], v162 offset:2048
	ds_read_b128 v[210:213], v162 offset:3072
	ds_read_b128 v[214:217], v162 offset:4096
	ds_read_b128 v[218:221], v162 offset:5120
	ds_read_b128 v[222:225], v162 offset:6144
	ds_read_b128 v[226:229], v162 offset:7168
	global_load_lds_dwordx4 v[140:141], off
	s_add_i32 m0, s35, 0xe000
	v_lshl_add_u64 v[140:141], s[24:25], 0, v[138:139]
	global_load_lds_dwordx4 v[140:141], off
	s_waitcnt lgkmcnt(8)
	s_barrier
	s_waitcnt lgkmcnt(0)
	v_mfma_f32_16x16x32_bf16 v[126:129], v[164:167], v[180:183], v[126:129]
	v_mfma_f32_16x16x32_bf16 v[122:125], v[172:175], v[180:183], v[122:125]
	v_mfma_f32_16x16x32_bf16 v[114:117], v[164:167], v[206:209], v[114:117]
	v_mfma_f32_16x16x32_bf16 v[106:109], v[172:175], v[206:209], v[106:109]
	v_mfma_f32_16x16x32_bf16 v[98:101], v[164:167], v[214:217], v[98:101]
	v_mfma_f32_16x16x32_bf16 v[90:93], v[172:175], v[214:217], v[90:93]
	v_mfma_f32_16x16x32_bf16 v[82:85], v[164:167], v[222:225], v[82:85]
	v_mfma_f32_16x16x32_bf16 v[74:77], v[172:175], v[222:225], v[74:77]
	v_mfma_f32_16x16x32_bf16 v[126:129], v[168:171], v[184:187], v[126:129]
	v_mfma_f32_16x16x32_bf16 v[122:125], v[176:179], v[184:187], v[122:125]
	v_mfma_f32_16x16x32_bf16 v[114:117], v[168:171], v[210:213], v[114:117]
	v_mfma_f32_16x16x32_bf16 v[106:109], v[176:179], v[210:213], v[106:109]
	v_mfma_f32_16x16x32_bf16 v[98:101], v[168:171], v[218:221], v[98:101]
	v_mfma_f32_16x16x32_bf16 v[90:93], v[176:179], v[218:221], v[90:93]
	v_mfma_f32_16x16x32_bf16 v[82:85], v[168:171], v[226:229], v[82:85]
	v_mfma_f32_16x16x32_bf16 v[74:77], v[176:179], v[226:229], v[74:77]
	s_barrier
	s_add_i32 s53, 0, 0x14000
	v_add_u32_e32 v140, s53, v144
	s_add_i32 s24, s52, s31
	ds_read_b128 v[230:233], v140
	ds_read_b128 v[234:237], v140 offset:1024
	ds_read_b128 v[238:241], v140 offset:2048
	ds_read_b128 v[242:245], v140 offset:3072
	v_lshl_add_u64 v[140:141], s[26:27], 0, v[0:1]
	s_mov_b32 m0, s24
	v_lshl_add_u64 v[246:247], s[26:27], 0, v[130:131]
	global_load_lds_dwordx4 v[140:141], off
	s_add_i32 m0, s24, 0x2000
	s_nop 0
	global_load_lds_dwordx4 v[246:247], off
	s_barrier
	s_waitcnt lgkmcnt(0)
	v_mfma_f32_16x16x32_bf16 v[118:121], v[230:233], v[180:183], v[118:121]
	v_mfma_f32_16x16x32_bf16 v[110:113], v[238:241], v[180:183], v[110:113]
	v_mfma_f32_16x16x32_bf16 v[102:105], v[230:233], v[206:209], v[102:105]
	v_mfma_f32_16x16x32_bf16 v[94:97], v[238:241], v[206:209], v[94:97]
	v_mfma_f32_16x16x32_bf16 v[86:89], v[230:233], v[214:217], v[86:89]
	v_mfma_f32_16x16x32_bf16 v[78:81], v[238:241], v[214:217], v[78:81]
	v_mfma_f32_16x16x32_bf16 v[70:73], v[230:233], v[222:225], v[70:73]
	v_mfma_f32_16x16x32_bf16 v[66:69], v[238:241], v[222:225], v[66:69]
	v_mfma_f32_16x16x32_bf16 v[118:121], v[234:237], v[184:187], v[118:121]
	v_mfma_f32_16x16x32_bf16 v[110:113], v[242:245], v[184:187], v[110:113]
	v_mfma_f32_16x16x32_bf16 v[102:105], v[234:237], v[210:213], v[102:105]
	v_mfma_f32_16x16x32_bf16 v[94:97], v[242:245], v[210:213], v[94:97]
	v_mfma_f32_16x16x32_bf16 v[86:89], v[234:237], v[218:221], v[86:89]
	v_mfma_f32_16x16x32_bf16 v[78:81], v[242:245], v[218:221], v[78:81]
	v_mfma_f32_16x16x32_bf16 v[70:73], v[234:237], v[226:229], v[70:73]
	v_mfma_f32_16x16x32_bf16 v[66:69], v[242:245], v[226:229], v[66:69]
	s_barrier
	s_mov_b32 m0, s35
	v_lshl_add_u64 v[248:249], s[28:29], 0, v[134:135]
	ds_read_b128 v[180:183], v162 offset:16384
	ds_read_b128 v[184:187], v162 offset:17408
	ds_read_b128 v[206:209], v162 offset:18432
	ds_read_b128 v[210:213], v162 offset:19456
	ds_read_b128 v[214:217], v162 offset:20480
	ds_read_b128 v[218:221], v162 offset:21504
	ds_read_b128 v[222:225], v162 offset:22528
	ds_read_b128 v[226:229], v162 offset:23552
	global_load_lds_dwordx4 v[248:249], off
	s_mov_b32 m0, s36
	v_lshl_add_u64 v[250:251], s[28:29], 0, v[132:133]
	global_load_lds_dwordx4 v[250:251], off
	s_barrier
	s_waitcnt lgkmcnt(0)
	v_mfma_f32_16x16x32_bf16 v[62:65], v[164:167], v[180:183], v[62:65]
	v_mfma_f32_16x16x32_bf16 v[58:61], v[172:175], v[180:183], v[58:61]
	v_mfma_f32_16x16x32_bf16 v[50:53], v[164:167], v[206:209], v[50:53]
	v_mfma_f32_16x16x32_bf16 v[42:45], v[172:175], v[206:209], v[42:45]
	v_mfma_f32_16x16x32_bf16 v[34:37], v[164:167], v[214:217], v[34:37]
	v_mfma_f32_16x16x32_bf16 v[26:29], v[172:175], v[214:217], v[26:29]
	v_mfma_f32_16x16x32_bf16 v[18:21], v[164:167], v[222:225], v[18:21]
	v_mfma_f32_16x16x32_bf16 v[10:13], v[172:175], v[222:225], v[10:13]
	v_mfma_f32_16x16x32_bf16 v[62:65], v[168:171], v[184:187], v[62:65]
	v_mfma_f32_16x16x32_bf16 v[58:61], v[176:179], v[184:187], v[58:61]
	v_mfma_f32_16x16x32_bf16 v[50:53], v[168:171], v[210:213], v[50:53]
	v_mfma_f32_16x16x32_bf16 v[42:45], v[176:179], v[210:213], v[42:45]
	v_mfma_f32_16x16x32_bf16 v[34:37], v[168:171], v[218:221], v[34:37]
	v_mfma_f32_16x16x32_bf16 v[26:29], v[176:179], v[218:221], v[26:29]
	v_mfma_f32_16x16x32_bf16 v[18:21], v[168:171], v[226:229], v[18:21]
	v_mfma_f32_16x16x32_bf16 v[10:13], v[176:179], v[226:229], v[10:13]
	s_barrier
	s_add_u32 s24, s26, 0xb0000
	s_addc_u32 s25, s27, 0
	s_add_i32 s52, s53, s31
	s_mov_b32 m0, s52
	v_lshl_add_u64 v[164:165], s[24:25], 0, v[0:1]
	global_load_lds_dwordx4 v[164:165], off
	s_add_i32 m0, s52, 0x2000
	v_lshl_add_u64 v[164:165], s[24:25], 0, v[130:131]
	global_load_lds_dwordx4 v[164:165], off
	s_waitcnt vmcnt(6)
	s_barrier
	v_mfma_f32_16x16x32_bf16 v[54:57], v[230:233], v[180:183], v[54:57]
	v_mfma_f32_16x16x32_bf16 v[46:49], v[238:241], v[180:183], v[46:49]
	v_mfma_f32_16x16x32_bf16 v[38:41], v[230:233], v[206:209], v[38:41]
	v_mfma_f32_16x16x32_bf16 v[30:33], v[238:241], v[206:209], v[30:33]
	v_mfma_f32_16x16x32_bf16 v[22:25], v[230:233], v[214:217], v[22:25]
	v_mfma_f32_16x16x32_bf16 v[14:17], v[238:241], v[214:217], v[14:17]
	v_mfma_f32_16x16x32_bf16 v[6:9], v[230:233], v[222:225], v[6:9]
	v_mfma_f32_16x16x32_bf16 v[2:5], v[238:241], v[222:225], v[2:5]
	v_mfma_f32_16x16x32_bf16 v[54:57], v[234:237], v[184:187], v[54:57]
	v_mfma_f32_16x16x32_bf16 v[46:49], v[242:245], v[184:187], v[46:49]
	v_mfma_f32_16x16x32_bf16 v[38:41], v[234:237], v[210:213], v[38:41]
	v_mfma_f32_16x16x32_bf16 v[30:33], v[242:245], v[210:213], v[30:33]
	v_mfma_f32_16x16x32_bf16 v[22:25], v[234:237], v[218:221], v[22:25]
	v_mfma_f32_16x16x32_bf16 v[14:17], v[242:245], v[218:221], v[14:17]
	v_mfma_f32_16x16x32_bf16 v[6:9], v[234:237], v[226:229], v[6:9]
	v_mfma_f32_16x16x32_bf16 v[2:5], v[242:245], v[226:229], v[2:5]
	s_barrier
	s_add_i32 s52, 0, 0x18000
	v_add_u32_e32 v163, s52, v144
	ds_read_b128 v[164:167], v163
	ds_read_b128 v[168:171], v163 offset:1024
	ds_read_b128 v[172:175], v163 offset:2048
	ds_read_b128 v[176:179], v163 offset:3072
	s_add_u32 s24, s28, 0xb0000
	s_addc_u32 s25, s29, 0
	s_mov_b32 m0, s37
	v_lshl_add_u64 v[230:231], s[24:25], 0, v[134:135]
	ds_read_b128 v[180:183], v162 offset:32768
	ds_read_b128 v[184:187], v162 offset:33792
	ds_read_b128 v[206:209], v162 offset:34816
	ds_read_b128 v[210:213], v162 offset:35840
	ds_read_b128 v[214:217], v162 offset:36864
	ds_read_b128 v[218:221], v162 offset:37888
	ds_read_b128 v[222:225], v162 offset:38912
	ds_read_b128 v[226:229], v162 offset:39936
	global_load_lds_dwordx4 v[230:231], off
	s_mov_b32 m0, s42
	v_lshl_add_u64 v[230:231], s[24:25], 0, v[132:133]
	global_load_lds_dwordx4 v[230:231], off
	s_waitcnt lgkmcnt(8)
	s_barrier
	s_waitcnt lgkmcnt(0)
	v_mfma_f32_16x16x32_bf16 v[126:129], v[164:167], v[180:183], v[126:129]
	v_mfma_f32_16x16x32_bf16 v[122:125], v[172:175], v[180:183], v[122:125]
	v_mfma_f32_16x16x32_bf16 v[114:117], v[164:167], v[206:209], v[114:117]
	v_mfma_f32_16x16x32_bf16 v[106:109], v[172:175], v[206:209], v[106:109]
	v_mfma_f32_16x16x32_bf16 v[98:101], v[164:167], v[214:217], v[98:101]
	v_mfma_f32_16x16x32_bf16 v[90:93], v[172:175], v[214:217], v[90:93]
	v_mfma_f32_16x16x32_bf16 v[82:85], v[164:167], v[222:225], v[82:85]
	v_mfma_f32_16x16x32_bf16 v[74:77], v[172:175], v[222:225], v[74:77]
	v_mfma_f32_16x16x32_bf16 v[126:129], v[168:171], v[184:187], v[126:129]
	v_mfma_f32_16x16x32_bf16 v[122:125], v[176:179], v[184:187], v[122:125]
	v_mfma_f32_16x16x32_bf16 v[114:117], v[168:171], v[210:213], v[114:117]
	v_mfma_f32_16x16x32_bf16 v[106:109], v[176:179], v[210:213], v[106:109]
	v_mfma_f32_16x16x32_bf16 v[98:101], v[168:171], v[218:221], v[98:101]
	v_mfma_f32_16x16x32_bf16 v[90:93], v[176:179], v[218:221], v[90:93]
	v_mfma_f32_16x16x32_bf16 v[82:85], v[168:171], v[226:229], v[82:85]
	v_mfma_f32_16x16x32_bf16 v[74:77], v[176:179], v[226:229], v[74:77]
	s_barrier
	s_add_i32 s28, 0, 0x1c000
	s_add_i32 s24, s52, s31
	v_add_u32_e32 v163, s28, v144
	v_lshl_add_u64 v[140:141], v[140:141], 0, s[94:95]
	s_mov_b32 m0, s24
	ds_read_b128 v[230:233], v163
	ds_read_b128 v[234:237], v163 offset:1024
	ds_read_b128 v[238:241], v163 offset:2048
	ds_read_b128 v[242:245], v163 offset:3072
	global_load_lds_dwordx4 v[140:141], off
	s_add_i32 m0, s24, 0x2000
	v_lshl_add_u64 v[140:141], v[246:247], 0, s[94:95]
	global_load_lds_dwordx4 v[140:141], off
	s_barrier
	s_waitcnt lgkmcnt(0)
	v_mfma_f32_16x16x32_bf16 v[118:121], v[230:233], v[180:183], v[118:121]
	v_mfma_f32_16x16x32_bf16 v[110:113], v[238:241], v[180:183], v[110:113]
	v_mfma_f32_16x16x32_bf16 v[102:105], v[230:233], v[206:209], v[102:105]
	v_mfma_f32_16x16x32_bf16 v[94:97], v[238:241], v[206:209], v[94:97]
	v_mfma_f32_16x16x32_bf16 v[86:89], v[230:233], v[214:217], v[86:89]
	v_mfma_f32_16x16x32_bf16 v[78:81], v[238:241], v[214:217], v[78:81]
	v_mfma_f32_16x16x32_bf16 v[70:73], v[230:233], v[222:225], v[70:73]
	v_mfma_f32_16x16x32_bf16 v[66:69], v[238:241], v[222:225], v[66:69]
	v_mfma_f32_16x16x32_bf16 v[118:121], v[234:237], v[184:187], v[118:121]
	v_mfma_f32_16x16x32_bf16 v[110:113], v[242:245], v[184:187], v[110:113]
	v_mfma_f32_16x16x32_bf16 v[102:105], v[234:237], v[210:213], v[102:105]
	v_mfma_f32_16x16x32_bf16 v[94:97], v[242:245], v[210:213], v[94:97]
	v_mfma_f32_16x16x32_bf16 v[86:89], v[234:237], v[218:221], v[86:89]
	v_mfma_f32_16x16x32_bf16 v[78:81], v[242:245], v[218:221], v[78:81]
	v_mfma_f32_16x16x32_bf16 v[70:73], v[234:237], v[226:229], v[70:73]
	v_mfma_f32_16x16x32_bf16 v[66:69], v[242:245], v[226:229], v[66:69]
	s_barrier
	s_mov_b32 m0, s44
	v_lshl_add_u64 v[140:141], v[248:249], 0, s[94:95]
	ds_read_b128 v[180:183], v162 offset:49152
	ds_read_b128 v[184:187], v162 offset:50176
	ds_read_b128 v[206:209], v162 offset:51200
	ds_read_b128 v[210:213], v162 offset:52224
	ds_read_b128 v[214:217], v162 offset:53248
	ds_read_b128 v[218:221], v162 offset:54272
	ds_read_b128 v[222:225], v162 offset:55296
	ds_read_b128 v[226:229], v162 offset:56320
	global_load_lds_dwordx4 v[140:141], off
	s_mov_b32 m0, s45
	v_lshl_add_u64 v[140:141], v[250:251], 0, s[94:95]
	global_load_lds_dwordx4 v[140:141], off
	s_barrier
	s_waitcnt lgkmcnt(0)
	v_mfma_f32_16x16x32_bf16 v[62:65], v[164:167], v[180:183], v[62:65]
	v_mfma_f32_16x16x32_bf16 v[58:61], v[172:175], v[180:183], v[58:61]
	v_mfma_f32_16x16x32_bf16 v[50:53], v[164:167], v[206:209], v[50:53]
	v_mfma_f32_16x16x32_bf16 v[42:45], v[172:175], v[206:209], v[42:45]
	v_mfma_f32_16x16x32_bf16 v[34:37], v[164:167], v[214:217], v[34:37]
	v_mfma_f32_16x16x32_bf16 v[26:29], v[172:175], v[214:217], v[26:29]
	v_mfma_f32_16x16x32_bf16 v[18:21], v[164:167], v[222:225], v[18:21]
	v_mfma_f32_16x16x32_bf16 v[10:13], v[172:175], v[222:225], v[10:13]
	v_mfma_f32_16x16x32_bf16 v[62:65], v[168:171], v[184:187], v[62:65]
	v_mfma_f32_16x16x32_bf16 v[58:61], v[176:179], v[184:187], v[58:61]
	v_mfma_f32_16x16x32_bf16 v[50:53], v[168:171], v[210:213], v[50:53]
	v_mfma_f32_16x16x32_bf16 v[42:45], v[176:179], v[210:213], v[42:45]
	v_mfma_f32_16x16x32_bf16 v[34:37], v[168:171], v[218:221], v[34:37]
	v_mfma_f32_16x16x32_bf16 v[26:29], v[176:179], v[218:221], v[26:29]
	v_mfma_f32_16x16x32_bf16 v[18:21], v[168:171], v[226:229], v[18:21]
	v_mfma_f32_16x16x32_bf16 v[10:13], v[176:179], v[226:229], v[10:13]
	s_barrier
	s_add_u32 s24, s26, 0xb0080
	s_addc_u32 s25, s27, 0
	s_add_i32 s26, s28, s31
	s_mov_b32 m0, s26
	v_lshl_add_u64 v[140:141], s[24:25], 0, v[0:1]
	global_load_lds_dwordx4 v[140:141], off
	s_add_i32 m0, s26, 0x2000
	v_lshl_add_u64 v[140:141], s[24:25], 0, v[130:131]
	global_load_lds_dwordx4 v[140:141], off
	s_waitcnt vmcnt(6)
	s_barrier
	v_mfma_f32_16x16x32_bf16 v[54:57], v[230:233], v[180:183], v[54:57]
	v_mfma_f32_16x16x32_bf16 v[46:49], v[238:241], v[180:183], v[46:49]
	v_mfma_f32_16x16x32_bf16 v[38:41], v[230:233], v[206:209], v[38:41]
	v_mfma_f32_16x16x32_bf16 v[30:33], v[238:241], v[206:209], v[30:33]
	v_mfma_f32_16x16x32_bf16 v[22:25], v[230:233], v[214:217], v[22:25]
	v_mfma_f32_16x16x32_bf16 v[14:17], v[238:241], v[214:217], v[14:17]
	v_mfma_f32_16x16x32_bf16 v[6:9], v[230:233], v[222:225], v[6:9]
	v_mfma_f32_16x16x32_bf16 v[2:5], v[238:241], v[222:225], v[2:5]
	v_mfma_f32_16x16x32_bf16 v[54:57], v[234:237], v[184:187], v[54:57]
	v_mfma_f32_16x16x32_bf16 v[46:49], v[242:245], v[184:187], v[46:49]
	v_mfma_f32_16x16x32_bf16 v[38:41], v[234:237], v[210:213], v[38:41]
	v_mfma_f32_16x16x32_bf16 v[30:33], v[242:245], v[210:213], v[30:33]
	v_mfma_f32_16x16x32_bf16 v[22:25], v[234:237], v[218:221], v[22:25]
	v_mfma_f32_16x16x32_bf16 v[14:17], v[242:245], v[218:221], v[14:17]
	v_mfma_f32_16x16x32_bf16 v[6:9], v[234:237], v[226:229], v[6:9]
	v_mfma_f32_16x16x32_bf16 v[2:5], v[242:245], v[226:229], v[2:5]
	s_barrier
	s_add_i32 s51, s51, 2
	s_add_u32 s40, s40, 0x100
	s_addc_u32 s41, s41, 0
	s_cmp_gt_u32 s51, 41
	s_mov_b64 s[24:25], s[22:23]
	s_cbranch_scc0 .LBB0_331
	v_lshl_or_b32 v140, s50, 8, v145
	v_lshl_add_u32 v164, s49, 8, v143
	v_ashrrev_i32_e32 v141, 31, v140
	v_ashrrev_i32_e32 v165, 31, v164
	v_lshl_add_u64 v[166:167], v[140:141], 1, s[20:21]
	v_lshlrev_b64 v[140:141], 11, v[164:165]
	v_lshl_add_u64 v[140:141], v[166:167], 0, v[140:141]
	v_pk_add_f32 v[128:129], v[128:129], 0 op_sel_hi:[1,0]
	v_pk_add_f32 v[126:127], v[126:127], 0 op_sel_hi:[1,0]
	v_pk_add_f32 v[168:169], v[124:125], 0 op_sel_hi:[1,0]
	v_pk_add_f32 v[124:125], v[122:123], 0 op_sel_hi:[1,0]
	v_cvt_pk_bf16_f32 v122, v126, v127
	v_cvt_pk_bf16_f32 v123, v128, v129
	v_pk_add_f32 v[118:119], v[118:119], 0 op_sel_hi:[1,0]
	v_cvt_pk_bf16_f32 v124, v124, v125
	v_cvt_pk_bf16_f32 v125, v168, v169
	global_store_dwordx4 v[140:141], v[122:125], off
	v_pk_add_f32 v[120:121], v[120:121], 0 op_sel_hi:[1,0]
	v_pk_add_f32 v[114:115], v[114:115], 0 op_sel_hi:[1,0]
	v_pk_add_f32 v[122:123], v[112:113], 0 op_sel_hi:[1,0]
	v_pk_add_f32 v[112:113], v[110:111], 0 op_sel_hi:[1,0]
	v_cvt_pk_bf16_f32 v110, v118, v119
	v_cvt_pk_bf16_f32 v111, v120, v121
	v_pk_add_f32 v[102:103], v[102:103], 0 op_sel_hi:[1,0]
	v_cvt_pk_bf16_f32 v112, v112, v113
	v_cvt_pk_bf16_f32 v113, v122, v123
	global_store_dwordx4 v[140:141], v[110:113], off offset:256
	v_pk_add_f32 v[104:105], v[104:105], 0 op_sel_hi:[1,0]
	v_pk_add_f32 v[98:99], v[98:99], 0 op_sel_hi:[1,0]
	v_or_b32_e32 v110, 16, v164
	v_ashrrev_i32_e32 v111, 31, v110
	v_lshlrev_b64 v[110:111], 11, v[110:111]
	v_lshl_add_u64 v[110:111], v[166:167], 0, v[110:111]
	v_pk_add_f32 v[112:113], v[116:117], 0 op_sel_hi:[1,0]
	v_pk_add_f32 v[116:117], v[108:109], 0 op_sel_hi:[1,0]
	v_pk_add_f32 v[108:109], v[106:107], 0 op_sel_hi:[1,0]
	v_cvt_pk_bf16_f32 v106, v114, v115
	v_cvt_pk_bf16_f32 v107, v112, v113
	v_pk_add_f32 v[86:87], v[86:87], 0 op_sel_hi:[1,0]
	v_cvt_pk_bf16_f32 v108, v108, v109
	v_cvt_pk_bf16_f32 v109, v116, v117
	global_store_dwordx4 v[110:111], v[106:109], off
	v_pk_add_f32 v[88:89], v[88:89], 0 op_sel_hi:[1,0]
	v_pk_add_f32 v[82:83], v[82:83], 0 op_sel_hi:[1,0]
	v_pk_add_f32 v[106:107], v[96:97], 0 op_sel_hi:[1,0]
	v_pk_add_f32 v[96:97], v[94:95], 0 op_sel_hi:[1,0]
	v_cvt_pk_bf16_f32 v94, v102, v103
	v_cvt_pk_bf16_f32 v95, v104, v105
	v_pk_add_f32 v[72:73], v[72:73], 0 op_sel_hi:[1,0]
	v_cvt_pk_bf16_f32 v96, v96, v97
	v_cvt_pk_bf16_f32 v97, v106, v107
	global_store_dwordx4 v[110:111], v[94:97], off offset:256
	v_pk_add_f32 v[70:71], v[70:71], 0 op_sel_hi:[1,0]
	v_pk_add_f32 v[62:63], v[62:63], 0 op_sel_hi:[1,0]
	v_or_b32_e32 v94, 32, v164
	v_ashrrev_i32_e32 v95, 31, v94
	v_lshlrev_b64 v[94:95], 11, v[94:95]
	v_lshl_add_u64 v[94:95], v[166:167], 0, v[94:95]
	v_pk_add_f32 v[96:97], v[100:101], 0 op_sel_hi:[1,0]
	v_pk_add_f32 v[100:101], v[92:93], 0 op_sel_hi:[1,0]
	v_pk_add_f32 v[92:93], v[90:91], 0 op_sel_hi:[1,0]
	v_cvt_pk_bf16_f32 v90, v98, v99
	v_cvt_pk_bf16_f32 v91, v96, v97
	v_pk_add_f32 v[64:65], v[64:65], 0 op_sel_hi:[1,0]
	v_cvt_pk_bf16_f32 v92, v92, v93
	v_cvt_pk_bf16_f32 v93, v100, v101
	global_store_dwordx4 v[94:95], v[90:93], off
	s_mov_b64 s[22:23], 0x40000
	v_pk_add_f32 v[56:57], v[56:57], 0 op_sel_hi:[1,0]
	v_pk_add_f32 v[90:91], v[80:81], 0 op_sel_hi:[1,0]
	v_pk_add_f32 v[80:81], v[78:79], 0 op_sel_hi:[1,0]
	v_cvt_pk_bf16_f32 v78, v86, v87
	v_cvt_pk_bf16_f32 v79, v88, v89
	v_pk_add_f32 v[54:55], v[54:55], 0 op_sel_hi:[1,0]
	v_cvt_pk_bf16_f32 v80, v80, v81
	v_cvt_pk_bf16_f32 v81, v90, v91
	global_store_dwordx4 v[94:95], v[78:81], off offset:256
	v_pk_add_f32 v[50:51], v[50:51], 0 op_sel_hi:[1,0]
	v_pk_add_f32 v[40:41], v[40:41], 0 op_sel_hi:[1,0]
	v_or_b32_e32 v78, 48, v164
	v_ashrrev_i32_e32 v79, 31, v78
	v_lshlrev_b64 v[78:79], 11, v[78:79]
	v_lshl_add_u64 v[78:79], v[166:167], 0, v[78:79]
	v_pk_add_f32 v[80:81], v[84:85], 0 op_sel_hi:[1,0]
	v_pk_add_f32 v[84:85], v[76:77], 0 op_sel_hi:[1,0]
	v_pk_add_f32 v[76:77], v[74:75], 0 op_sel_hi:[1,0]
	v_cvt_pk_bf16_f32 v74, v82, v83
	v_cvt_pk_bf16_f32 v75, v80, v81
	v_pk_add_f32 v[38:39], v[38:39], 0 op_sel_hi:[1,0]
	v_cvt_pk_bf16_f32 v76, v76, v77
	v_cvt_pk_bf16_f32 v77, v84, v85
	global_store_dwordx4 v[78:79], v[74:77], off
	v_pk_add_f32 v[34:35], v[34:35], 0 op_sel_hi:[1,0]
	v_pk_add_f32 v[24:25], v[24:25], 0 op_sel_hi:[1,0]
	v_pk_add_f32 v[74:75], v[68:69], 0 op_sel_hi:[1,0]
	v_pk_add_f32 v[68:69], v[66:67], 0 op_sel_hi:[1,0]
	v_cvt_pk_bf16_f32 v66, v70, v71
	v_cvt_pk_bf16_f32 v67, v72, v73
	v_pk_add_f32 v[22:23], v[22:23], 0 op_sel_hi:[1,0]
	v_cvt_pk_bf16_f32 v68, v68, v69
	v_cvt_pk_bf16_f32 v69, v74, v75
	global_store_dwordx4 v[78:79], v[66:69], off offset:256
	v_pk_add_f32 v[18:19], v[18:19], 0 op_sel_hi:[1,0]
	s_mov_b32 s50, s47
	v_pk_add_f32 v[68:69], v[60:61], 0 op_sel_hi:[1,0]
	v_pk_add_f32 v[60:61], v[58:59], 0 op_sel_hi:[1,0]
	v_cvt_pk_bf16_f32 v58, v62, v63
	v_add_co_u32_e32 v62, vcc, s67, v140
	v_cvt_pk_bf16_f32 v59, v64, v65
	v_cvt_pk_bf16_f32 v60, v60, v61
	v_cvt_pk_bf16_f32 v61, v68, v69
	v_lshl_add_u64 v[66:67], v[140:141], 0, s[22:23]
	s_nop 0
	v_addc_co_u32_e32 v63, vcc, 0, v141, vcc
	global_store_dwordx4 v[62:63], v[58:61], off
	s_mov_b64 s[22:23], 0x48000
	s_mov_b32 s49, s48
	v_pk_add_f32 v[58:59], v[48:49], 0 op_sel_hi:[1,0]
	v_pk_add_f32 v[48:49], v[46:47], 0 op_sel_hi:[1,0]
	v_cvt_pk_bf16_f32 v46, v54, v55
	v_cvt_pk_bf16_f32 v47, v56, v57
	s_mov_b64 s[24:25], s[2:3]
	v_cvt_pk_bf16_f32 v48, v48, v49
	v_cvt_pk_bf16_f32 v49, v58, v59
	global_store_dwordx4 v[66:67], v[46:49], off offset:256
	v_pk_add_f32 v[8:9], v[8:9], 0 op_sel_hi:[1,0]
	v_pk_add_f32 v[6:7], v[6:7], 0 op_sel_hi:[1,0]
	v_pk_add_f32 v[48:49], v[52:53], 0 op_sel_hi:[1,0]
	v_pk_add_f32 v[52:53], v[44:45], 0 op_sel_hi:[1,0]
	v_pk_add_f32 v[44:45], v[42:43], 0 op_sel_hi:[1,0]
	v_cvt_pk_bf16_f32 v42, v50, v51
	v_cvt_pk_bf16_f32 v43, v48, v49
	v_add_co_u32_e32 v48, vcc, s68, v140
	v_cvt_pk_bf16_f32 v44, v44, v45
	v_cvt_pk_bf16_f32 v45, v52, v53
	v_lshl_add_u64 v[46:47], v[140:141], 0, s[22:23]
	s_nop 0
	v_addc_co_u32_e32 v49, vcc, 0, v141, vcc
	global_store_dwordx4 v[48:49], v[42:45], off
	s_mov_b64 s[22:23], 0x50000
	s_nop 0
	v_pk_add_f32 v[42:43], v[32:33], 0 op_sel_hi:[1,0]
	v_pk_add_f32 v[32:33], v[30:31], 0 op_sel_hi:[1,0]
	v_cvt_pk_bf16_f32 v30, v38, v39
	v_cvt_pk_bf16_f32 v31, v40, v41
	s_nop 0
	v_cvt_pk_bf16_f32 v32, v32, v33
	v_cvt_pk_bf16_f32 v33, v42, v43
	global_store_dwordx4 v[46:47], v[30:33], off offset:256
	s_nop 1
	v_lshl_add_u64 v[30:31], v[140:141], 0, s[22:23]
	v_pk_add_f32 v[32:33], v[36:37], 0 op_sel_hi:[1,0]
	s_mov_b32 s22, 0x50000
	v_pk_add_f32 v[36:37], v[28:29], 0 op_sel_hi:[1,0]
	v_pk_add_f32 v[28:29], v[26:27], 0 op_sel_hi:[1,0]
	v_cvt_pk_bf16_f32 v26, v34, v35
	v_cvt_pk_bf16_f32 v27, v32, v33
	v_add_co_u32_e32 v32, vcc, s22, v140
	v_cvt_pk_bf16_f32 v28, v28, v29
	v_cvt_pk_bf16_f32 v29, v36, v37
	s_mov_b64 s[22:23], 0x58000
	s_nop 0
	v_addc_co_u32_e32 v33, vcc, 0, v141, vcc
	global_store_dwordx4 v[32:33], v[26:29], off
	s_nop 1
	v_pk_add_f32 v[26:27], v[16:17], 0 op_sel_hi:[1,0]
	v_pk_add_f32 v[16:17], v[14:15], 0 op_sel_hi:[1,0]
	v_cvt_pk_bf16_f32 v14, v22, v23
	v_cvt_pk_bf16_f32 v15, v24, v25
	s_nop 0
	v_cvt_pk_bf16_f32 v16, v16, v17
	v_cvt_pk_bf16_f32 v17, v26, v27
	global_store_dwordx4 v[30:31], v[14:17], off offset:256
	s_nop 1
	v_lshl_add_u64 v[14:15], v[140:141], 0, s[22:23]
	v_pk_add_f32 v[16:17], v[20:21], 0 op_sel_hi:[1,0]
	s_mov_b32 s22, 0x58000
	v_pk_add_f32 v[20:21], v[12:13], 0 op_sel_hi:[1,0]
	v_pk_add_f32 v[12:13], v[10:11], 0 op_sel_hi:[1,0]
	v_cvt_pk_bf16_f32 v10, v18, v19
	v_cvt_pk_bf16_f32 v11, v16, v17
	v_add_co_u32_e32 v16, vcc, s22, v140
	v_cvt_pk_bf16_f32 v12, v12, v13
	v_cvt_pk_bf16_f32 v13, v20, v21
	s_mov_b64 s[22:23], s[0:1]
	s_nop 0
	v_addc_co_u32_e32 v17, vcc, 0, v141, vcc
	global_store_dwordx4 v[16:17], v[10:13], off
	s_and_b64 vcc, exec, s[38:39]
	s_nop 0
	v_pk_add_f32 v[10:11], v[4:5], 0 op_sel_hi:[1,0]
	v_pk_add_f32 v[4:5], v[2:3], 0 op_sel_hi:[1,0]
	v_cvt_pk_bf16_f32 v2, v6, v7
	v_cvt_pk_bf16_f32 v3, v8, v9
	s_nop 0
	v_cvt_pk_bf16_f32 v4, v4, v5
	v_cvt_pk_bf16_f32 v5, v10, v11
	global_store_dwordx4 v[14:15], v[2:5], off offset:256
	s_cbranch_vccz .LBB0_320
	s_waitcnt vmcnt(16)
	s_cmpk_gt_u32 s30, 0xff
	s_cbranch_scc1 .LBB0_335
	s_barrier

.Lkprio_1:
.LBB0_360:
	s_add_u32 s44, s42, 0xfffc0080
	s_addc_u32 s45, s43, -1
	s_add_i32 s63, 0, 0x10000
	v_add_u32_e32 v0, s63, v206
	ds_read_b128 v[82:85], v0
	ds_read_b128 v[86:89], v0 offset:1024
	ds_read_b128 v[90:93], v0 offset:2048
	ds_read_b128 v[94:97], v0 offset:3072
	s_cmp_eq_u32 s62, 12
	s_cselect_b32 s47, s1, s45
	s_cselect_b32 s46, s3, s44
	s_cselect_b32 s45, s31, s61
	s_cselect_b32 s44, s35, s60
	v_lshl_add_u64 v[230:231], s[42:43], 0, v[174:175]
	s_add_i32 m0, s51, 0xc000
	ds_read_b128 v[176:179], v208
	ds_read_b128 v[180:183], v208 offset:1024
	ds_read_b128 v[184:187], v208 offset:2048
	ds_read_b128 v[210:213], v208 offset:3072
	ds_read_b128 v[214:217], v208 offset:4096
	ds_read_b128 v[218:221], v208 offset:5120
	ds_read_b128 v[222:225], v208 offset:6144
	ds_read_b128 v[226:229], v208 offset:7168
	global_load_lds_dwordx4 v[230:231], off
	s_add_i32 m0, s51, 0xe000
	v_lshl_add_u64 v[230:231], s[42:43], 0, v[172:173]
	global_load_lds_dwordx4 v[230:231], off
	s_waitcnt lgkmcnt(8)
	s_barrier
	s_waitcnt lgkmcnt(0)
	v_mfma_f32_16x16x32_bf16 v[142:145], v[82:85], v[176:179], v[142:145]
	v_mfma_f32_16x16x32_bf16 v[138:141], v[90:93], v[176:179], v[138:141]
	v_mfma_f32_16x16x32_bf16 v[126:129], v[82:85], v[184:187], v[126:129]
	v_mfma_f32_16x16x32_bf16 v[122:125], v[90:93], v[184:187], v[122:125]
	v_mfma_f32_16x16x32_bf16 v[110:113], v[82:85], v[214:217], v[110:113]
	v_mfma_f32_16x16x32_bf16 v[106:109], v[90:93], v[214:217], v[106:109]
	v_mfma_f32_16x16x32_bf16 v[78:81], v[82:85], v[222:225], v[78:81]
	v_mfma_f32_16x16x32_bf16 v[74:77], v[90:93], v[222:225], v[74:77]
	v_mfma_f32_16x16x32_bf16 v[142:145], v[86:89], v[180:183], v[142:145]
	v_mfma_f32_16x16x32_bf16 v[138:141], v[94:97], v[180:183], v[138:141]
	v_mfma_f32_16x16x32_bf16 v[126:129], v[86:89], v[210:213], v[126:129]
	v_mfma_f32_16x16x32_bf16 v[122:125], v[94:97], v[210:213], v[122:125]
	v_mfma_f32_16x16x32_bf16 v[110:113], v[86:89], v[218:221], v[110:113]
	v_mfma_f32_16x16x32_bf16 v[106:109], v[94:97], v[218:221], v[106:109]
	v_mfma_f32_16x16x32_bf16 v[78:81], v[86:89], v[226:229], v[78:81]
	v_mfma_f32_16x16x32_bf16 v[74:77], v[94:97], v[226:229], v[74:77]
	s_barrier
	s_add_i32 s66, 0, 0x14000
	s_add_i32 s63, s63, s50
	v_add_u32_e32 v0, s66, v206
	v_lshl_add_u64 v[246:247], s[44:45], 0, v[164:165]
	s_mov_b32 m0, s63
	ds_read_b128 v[230:233], v0
	ds_read_b128 v[234:237], v0 offset:1024
	ds_read_b128 v[238:241], v0 offset:2048
	ds_read_b128 v[242:245], v0 offset:3072
	global_load_lds_dwordx4 v[246:247], off
	s_add_i32 m0, s63, 0x2000
	v_lshl_add_u64 v[248:249], s[44:45], 0, v[168:169]
	global_load_lds_dwordx4 v[248:249], off
	s_barrier
	s_waitcnt lgkmcnt(0)
	v_mfma_f32_16x16x32_bf16 v[134:137], v[230:233], v[176:179], v[134:137]
	v_mfma_f32_16x16x32_bf16 v[130:133], v[238:241], v[176:179], v[130:133]
	v_mfma_f32_16x16x32_bf16 v[118:121], v[230:233], v[184:187], v[118:121]
	v_mfma_f32_16x16x32_bf16 v[114:117], v[238:241], v[184:187], v[114:117]
	v_mfma_f32_16x16x32_bf16 v[102:105], v[230:233], v[214:217], v[102:105]
	v_mfma_f32_16x16x32_bf16 v[98:101], v[238:241], v[214:217], v[98:101]
	v_mfma_f32_16x16x32_bf16 v[70:73], v[230:233], v[222:225], v[70:73]
	v_mfma_f32_16x16x32_bf16 v[66:69], v[238:241], v[222:225], v[66:69]
	v_mfma_f32_16x16x32_bf16 v[134:137], v[234:237], v[180:183], v[134:137]
	v_mfma_f32_16x16x32_bf16 v[130:133], v[242:245], v[180:183], v[130:133]
	v_mfma_f32_16x16x32_bf16 v[118:121], v[234:237], v[210:213], v[118:121]
	v_mfma_f32_16x16x32_bf16 v[114:117], v[242:245], v[210:213], v[114:117]
	v_mfma_f32_16x16x32_bf16 v[102:105], v[234:237], v[218:221], v[102:105]
	v_mfma_f32_16x16x32_bf16 v[98:101], v[242:245], v[218:221], v[98:101]
	v_mfma_f32_16x16x32_bf16 v[70:73], v[234:237], v[226:229], v[70:73]
	v_mfma_f32_16x16x32_bf16 v[66:69], v[242:245], v[226:229], v[66:69]
	s_barrier
	s_mov_b32 m0, s51
	v_lshl_add_u64 v[250:251], s[46:47], 0, v[162:163]
	ds_read_b128 v[176:179], v208 offset:16384
	ds_read_b128 v[180:183], v208 offset:17408
	ds_read_b128 v[184:187], v208 offset:18432
	ds_read_b128 v[210:213], v208 offset:19456
	ds_read_b128 v[214:217], v208 offset:20480
	ds_read_b128 v[218:221], v208 offset:21504
	ds_read_b128 v[222:225], v208 offset:22528
	ds_read_b128 v[226:229], v208 offset:23552
	global_load_lds_dwordx4 v[250:251], off
	s_mov_b32 m0, s52
	v_lshl_add_u64 v[252:253], s[46:47], 0, v[166:167]
	global_load_lds_dwordx4 v[252:253], off
	s_barrier
	s_waitcnt lgkmcnt(0)
	v_mfma_f32_16x16x32_bf16 v[62:65], v[82:85], v[176:179], v[62:65]
	v_mfma_f32_16x16x32_bf16 v[58:61], v[90:93], v[176:179], v[58:61]
	v_mfma_f32_16x16x32_bf16 v[46:49], v[82:85], v[184:187], v[46:49]
	v_mfma_f32_16x16x32_bf16 v[42:45], v[90:93], v[184:187], v[42:45]
	v_mfma_f32_16x16x32_bf16 v[30:33], v[82:85], v[214:217], v[30:33]
	v_mfma_f32_16x16x32_bf16 v[26:29], v[90:93], v[214:217], v[26:29]
	v_mfma_f32_16x16x32_bf16 v[14:17], v[82:85], v[222:225], v[14:17]
	v_mfma_f32_16x16x32_bf16 v[10:13], v[90:93], v[222:225], v[10:13]
	v_mfma_f32_16x16x32_bf16 v[62:65], v[86:89], v[180:183], v[62:65]
	v_mfma_f32_16x16x32_bf16 v[58:61], v[94:97], v[180:183], v[58:61]
	v_mfma_f32_16x16x32_bf16 v[46:49], v[86:89], v[210:213], v[46:49]
	v_mfma_f32_16x16x32_bf16 v[42:45], v[94:97], v[210:213], v[42:45]
	v_mfma_f32_16x16x32_bf16 v[30:33], v[86:89], v[218:221], v[30:33]
	v_mfma_f32_16x16x32_bf16 v[26:29], v[94:97], v[218:221], v[26:29]
	v_mfma_f32_16x16x32_bf16 v[14:17], v[86:89], v[226:229], v[14:17]
	v_mfma_f32_16x16x32_bf16 v[10:13], v[94:97], v[226:229], v[10:13]
	s_barrier
	s_add_u32 s64, s44, 0x40000
	s_addc_u32 s65, s45, 0
	s_add_i32 s63, s66, s50
	s_mov_b32 m0, s63
	v_lshl_add_u64 v[82:83], s[64:65], 0, v[164:165]
	global_load_lds_dwordx4 v[82:83], off
	s_add_i32 m0, s63, 0x2000
	v_lshl_add_u64 v[82:83], s[64:65], 0, v[168:169]
	global_load_lds_dwordx4 v[82:83], off
	s_waitcnt vmcnt(6)
	s_barrier
	v_mfma_f32_16x16x32_bf16 v[54:57], v[230:233], v[176:179], v[54:57]
	v_mfma_f32_16x16x32_bf16 v[50:53], v[238:241], v[176:179], v[50:53]
	v_mfma_f32_16x16x32_bf16 v[38:41], v[230:233], v[184:187], v[38:41]
	v_mfma_f32_16x16x32_bf16 v[34:37], v[238:241], v[184:187], v[34:37]
	v_mfma_f32_16x16x32_bf16 v[22:25], v[230:233], v[214:217], v[22:25]
	v_mfma_f32_16x16x32_bf16 v[18:21], v[238:241], v[214:217], v[18:21]
	v_mfma_f32_16x16x32_bf16 v[6:9], v[230:233], v[222:225], v[6:9]
	v_mfma_f32_16x16x32_bf16 v[2:5], v[238:241], v[222:225], v[2:5]
	v_mfma_f32_16x16x32_bf16 v[54:57], v[234:237], v[180:183], v[54:57]
	v_mfma_f32_16x16x32_bf16 v[50:53], v[242:245], v[180:183], v[50:53]
	v_mfma_f32_16x16x32_bf16 v[38:41], v[234:237], v[210:213], v[38:41]
	v_mfma_f32_16x16x32_bf16 v[34:37], v[242:245], v[210:213], v[34:37]
	v_mfma_f32_16x16x32_bf16 v[22:25], v[234:237], v[218:221], v[22:25]
	v_mfma_f32_16x16x32_bf16 v[18:21], v[242:245], v[218:221], v[18:21]
	v_mfma_f32_16x16x32_bf16 v[6:9], v[234:237], v[226:229], v[6:9]
	v_mfma_f32_16x16x32_bf16 v[2:5], v[242:245], v[226:229], v[2:5]
	s_barrier
	s_add_i32 s63, 0, 0x18000
	v_add_u32_e32 v0, s63, v206
	ds_read_b128 v[82:85], v0
	ds_read_b128 v[86:89], v0 offset:1024
	ds_read_b128 v[90:93], v0 offset:2048
	ds_read_b128 v[94:97], v0 offset:3072
	s_add_u32 s46, s46, 0x40000
	s_addc_u32 s47, s47, 0
	s_mov_b32 m0, s53
	v_lshl_add_u64 v[230:231], s[46:47], 0, v[162:163]
	ds_read_b128 v[176:179], v208 offset:32768
	ds_read_b128 v[180:183], v208 offset:33792
	ds_read_b128 v[184:187], v208 offset:34816
	ds_read_b128 v[210:213], v208 offset:35840
	ds_read_b128 v[214:217], v208 offset:36864
	ds_read_b128 v[218:221], v208 offset:37888
	ds_read_b128 v[222:225], v208 offset:38912
	ds_read_b128 v[226:229], v208 offset:39936
	global_load_lds_dwordx4 v[230:231], off
	s_mov_b32 m0, s54
	v_lshl_add_u64 v[230:231], s[46:47], 0, v[166:167]
	global_load_lds_dwordx4 v[230:231], off
	s_waitcnt lgkmcnt(8)
	s_barrier
	s_waitcnt lgkmcnt(0)
	v_mfma_f32_16x16x32_bf16 v[142:145], v[82:85], v[176:179], v[142:145]
	v_mfma_f32_16x16x32_bf16 v[138:141], v[90:93], v[176:179], v[138:141]
	v_mfma_f32_16x16x32_bf16 v[126:129], v[82:85], v[184:187], v[126:129]
	v_mfma_f32_16x16x32_bf16 v[122:125], v[90:93], v[184:187], v[122:125]
	v_mfma_f32_16x16x32_bf16 v[110:113], v[82:85], v[214:217], v[110:113]
	v_mfma_f32_16x16x32_bf16 v[106:109], v[90:93], v[214:217], v[106:109]
	v_mfma_f32_16x16x32_bf16 v[78:81], v[82:85], v[222:225], v[78:81]
	v_mfma_f32_16x16x32_bf16 v[74:77], v[90:93], v[222:225], v[74:77]
	v_mfma_f32_16x16x32_bf16 v[142:145], v[86:89], v[180:183], v[142:145]
	v_mfma_f32_16x16x32_bf16 v[138:141], v[94:97], v[180:183], v[138:141]
	v_mfma_f32_16x16x32_bf16 v[126:129], v[86:89], v[210:213], v[126:129]
	v_mfma_f32_16x16x32_bf16 v[122:125], v[94:97], v[210:213], v[122:125]
	v_mfma_f32_16x16x32_bf16 v[110:113], v[86:89], v[218:221], v[110:113]
	v_mfma_f32_16x16x32_bf16 v[106:109], v[94:97], v[218:221], v[106:109]
	v_mfma_f32_16x16x32_bf16 v[78:81], v[86:89], v[226:229], v[78:81]
	v_mfma_f32_16x16x32_bf16 v[74:77], v[94:97], v[226:229], v[74:77]
	s_barrier
	s_add_i32 s46, 0, 0x1c000
	s_add_i32 s47, s63, s50
	v_add_u32_e32 v0, s46, v206
	v_lshl_add_u64 v[246:247], v[246:247], 0, s[94:95]
	s_mov_b32 m0, s47
	ds_read_b128 v[230:233], v0
	ds_read_b128 v[234:237], v0 offset:1024
	ds_read_b128 v[238:241], v0 offset:2048
	ds_read_b128 v[242:245], v0 offset:3072
	global_load_lds_dwordx4 v[246:247], off
	s_add_i32 m0, s47, 0x2000
	v_lshl_add_u64 v[246:247], v[248:249], 0, s[94:95]
	global_load_lds_dwordx4 v[246:247], off
	s_barrier
	s_waitcnt lgkmcnt(0)
	v_mfma_f32_16x16x32_bf16 v[134:137], v[230:233], v[176:179], v[134:137]
	v_mfma_f32_16x16x32_bf16 v[130:133], v[238:241], v[176:179], v[130:133]
	v_mfma_f32_16x16x32_bf16 v[118:121], v[230:233], v[184:187], v[118:121]
	v_mfma_f32_16x16x32_bf16 v[114:117], v[238:241], v[184:187], v[114:117]
	v_mfma_f32_16x16x32_bf16 v[102:105], v[230:233], v[214:217], v[102:105]
	v_mfma_f32_16x16x32_bf16 v[98:101], v[238:241], v[214:217], v[98:101]
	v_mfma_f32_16x16x32_bf16 v[70:73], v[230:233], v[222:225], v[70:73]
	v_mfma_f32_16x16x32_bf16 v[66:69], v[238:241], v[222:225], v[66:69]
	v_mfma_f32_16x16x32_bf16 v[134:137], v[234:237], v[180:183], v[134:137]
	v_mfma_f32_16x16x32_bf16 v[130:133], v[242:245], v[180:183], v[130:133]
	v_mfma_f32_16x16x32_bf16 v[118:121], v[234:237], v[210:213], v[118:121]
	v_mfma_f32_16x16x32_bf16 v[114:117], v[242:245], v[210:213], v[114:117]
	v_mfma_f32_16x16x32_bf16 v[102:105], v[234:237], v[218:221], v[102:105]
	v_mfma_f32_16x16x32_bf16 v[98:101], v[242:245], v[218:221], v[98:101]
	v_mfma_f32_16x16x32_bf16 v[70:73], v[234:237], v[226:229], v[70:73]
	v_mfma_f32_16x16x32_bf16 v[66:69], v[242:245], v[226:229], v[66:69]
	s_barrier
	s_mov_b32 m0, s56
	v_lshl_add_u64 v[246:247], v[250:251], 0, s[94:95]
	ds_read_b128 v[176:179], v208 offset:49152
	ds_read_b128 v[180:183], v208 offset:50176
	ds_read_b128 v[184:187], v208 offset:51200
	ds_read_b128 v[210:213], v208 offset:52224
	ds_read_b128 v[214:217], v208 offset:53248
	ds_read_b128 v[218:221], v208 offset:54272
	ds_read_b128 v[222:225], v208 offset:55296
	ds_read_b128 v[226:229], v208 offset:56320
	global_load_lds_dwordx4 v[246:247], off
	s_mov_b32 m0, s57
	v_lshl_add_u64 v[246:247], v[252:253], 0, s[94:95]
	global_load_lds_dwordx4 v[246:247], off
	s_barrier
	s_waitcnt lgkmcnt(0)
	v_mfma_f32_16x16x32_bf16 v[62:65], v[82:85], v[176:179], v[62:65]
	v_mfma_f32_16x16x32_bf16 v[58:61], v[90:93], v[176:179], v[58:61]
	v_mfma_f32_16x16x32_bf16 v[46:49], v[82:85], v[184:187], v[46:49]
	v_mfma_f32_16x16x32_bf16 v[42:45], v[90:93], v[184:187], v[42:45]
	v_mfma_f32_16x16x32_bf16 v[30:33], v[82:85], v[214:217], v[30:33]
	v_mfma_f32_16x16x32_bf16 v[26:29], v[90:93], v[214:217], v[26:29]
	v_mfma_f32_16x16x32_bf16 v[14:17], v[82:85], v[222:225], v[14:17]
	v_mfma_f32_16x16x32_bf16 v[10:13], v[90:93], v[222:225], v[10:13]
	v_mfma_f32_16x16x32_bf16 v[62:65], v[86:89], v[180:183], v[62:65]
	v_mfma_f32_16x16x32_bf16 v[58:61], v[94:97], v[180:183], v[58:61]
	v_mfma_f32_16x16x32_bf16 v[46:49], v[86:89], v[210:213], v[46:49]
	v_mfma_f32_16x16x32_bf16 v[42:45], v[94:97], v[210:213], v[42:45]
	v_mfma_f32_16x16x32_bf16 v[30:33], v[86:89], v[218:221], v[30:33]
	v_mfma_f32_16x16x32_bf16 v[26:29], v[94:97], v[218:221], v[26:29]
	v_mfma_f32_16x16x32_bf16 v[14:17], v[86:89], v[226:229], v[14:17]
	v_mfma_f32_16x16x32_bf16 v[10:13], v[94:97], v[226:229], v[10:13]
	s_barrier
	s_add_u32 s44, s44, 0x40080
	s_addc_u32 s45, s45, 0
	s_add_i32 s46, s46, s50
	s_mov_b32 m0, s46
	v_lshl_add_u64 v[82:83], s[44:45], 0, v[164:165]
	global_load_lds_dwordx4 v[82:83], off
	s_add_i32 m0, s46, 0x2000
	v_lshl_add_u64 v[82:83], s[44:45], 0, v[168:169]
	global_load_lds_dwordx4 v[82:83], off
	s_waitcnt vmcnt(6)
	s_barrier
	v_mfma_f32_16x16x32_bf16 v[54:57], v[230:233], v[176:179], v[54:57]
	v_mfma_f32_16x16x32_bf16 v[50:53], v[238:241], v[176:179], v[50:53]
	v_mfma_f32_16x16x32_bf16 v[38:41], v[230:233], v[184:187], v[38:41]
	v_mfma_f32_16x16x32_bf16 v[34:37], v[238:241], v[184:187], v[34:37]
	v_mfma_f32_16x16x32_bf16 v[22:25], v[230:233], v[214:217], v[22:25]
	v_mfma_f32_16x16x32_bf16 v[18:21], v[238:241], v[214:217], v[18:21]
	v_mfma_f32_16x16x32_bf16 v[6:9], v[230:233], v[222:225], v[6:9]
	v_mfma_f32_16x16x32_bf16 v[2:5], v[238:241], v[222:225], v[2:5]
	v_mfma_f32_16x16x32_bf16 v[54:57], v[234:237], v[180:183], v[54:57]
	v_mfma_f32_16x16x32_bf16 v[50:53], v[242:245], v[180:183], v[50:53]
	v_mfma_f32_16x16x32_bf16 v[38:41], v[234:237], v[210:213], v[38:41]
	v_mfma_f32_16x16x32_bf16 v[34:37], v[242:245], v[210:213], v[34:37]
	v_mfma_f32_16x16x32_bf16 v[22:25], v[234:237], v[218:221], v[22:25]
	v_mfma_f32_16x16x32_bf16 v[18:21], v[242:245], v[218:221], v[18:21]
	v_mfma_f32_16x16x32_bf16 v[6:9], v[234:237], v[226:229], v[6:9]
	v_mfma_f32_16x16x32_bf16 v[2:5], v[242:245], v[226:229], v[2:5]
	s_barrier
	s_add_i32 s62, s62, 2
	s_add_u32 s60, s60, 0x100
	s_addc_u32 s61, s61, 0
	s_add_u32 s42, s42, 0x100
	s_addc_u32 s43, s43, 0
	s_cmp_gt_u32 s62, 13
	s_cbranch_scc0 .LBB0_360
	v_lshl_or_b32 v180, s0, 8, v207
	v_ashrrev_i32_e32 v181, 31, v180
	v_mov_b32_e32 v86, 0
	v_cndmask_b32_e64 v0, 0, 1, s[26:27]
	v_lshl_add_u64 v[176:177], v[180:181], 2, s[22:23]
	v_cmp_ne_u32_e64 s[0:1], 1, v0
	s_andn2_b64 vcc, exec, s[26:27]
	v_mov_b32_e32 v94, 0
	v_mov_b32_e32 v95, v86
	v_mov_b32_e32 v96, 0
	v_mov_b32_e32 v97, 0
	s_cbranch_vccnz .LBB0_363
	global_load_dwordx4 v[94:97], v[176:177], off

.Lkprio_0:
.LBB0_586:
	s_add_u32 s22, s20, 0xfffc0080
	s_addc_u32 s23, s21, -1
	s_add_i32 s48, 0, 0x10000
	v_add_u32_e32 v140, s48, v143
	ds_read_b128 v[162:165], v140
	ds_read_b128 v[166:169], v140 offset:1024
	ds_read_b128 v[170:173], v140 offset:2048
	ds_read_b128 v[174:177], v140 offset:3072
	s_cmp_eq_u32 s47, 12
	s_cselect_b32 s25, s9, s23
	s_cselect_b32 s24, s43, s22
	s_cselect_b32 s23, s1, s46
	s_cselect_b32 s22, s44, s45
	v_lshl_add_u64 v[140:141], s[20:21], 0, v[136:137]
	s_add_i32 m0, s3, 0xc000
	ds_read_b128 v[178:181], v145
	ds_read_b128 v[182:185], v145 offset:1024
	ds_read_b128 v[206:209], v145 offset:2048
	ds_read_b128 v[210:213], v145 offset:3072
	ds_read_b128 v[214:217], v145 offset:4096
	ds_read_b128 v[218:221], v145 offset:5120
	ds_read_b128 v[222:225], v145 offset:6144
	ds_read_b128 v[226:229], v145 offset:7168
	global_load_lds_dwordx4 v[140:141], off
	s_add_i32 m0, s3, 0xe000
	v_lshl_add_u64 v[140:141], s[20:21], 0, v[138:139]
	global_load_lds_dwordx4 v[140:141], off
	s_waitcnt lgkmcnt(8)
	s_barrier
	s_waitcnt lgkmcnt(0)
	v_mfma_f32_16x16x32_bf16 v[122:125], v[162:165], v[178:181], v[122:125]
	v_mfma_f32_16x16x32_bf16 v[114:117], v[170:173], v[178:181], v[114:117]
	v_mfma_f32_16x16x32_bf16 v[106:109], v[162:165], v[206:209], v[106:109]
	v_mfma_f32_16x16x32_bf16 v[98:101], v[170:173], v[206:209], v[98:101]
	v_mfma_f32_16x16x32_bf16 v[90:93], v[162:165], v[214:217], v[90:93]
	v_mfma_f32_16x16x32_bf16 v[82:85], v[170:173], v[214:217], v[82:85]
	v_mfma_f32_16x16x32_bf16 v[74:77], v[162:165], v[222:225], v[74:77]
	v_mfma_f32_16x16x32_bf16 v[66:69], v[170:173], v[222:225], v[66:69]
	v_mfma_f32_16x16x32_bf16 v[122:125], v[166:169], v[182:185], v[122:125]
	v_mfma_f32_16x16x32_bf16 v[114:117], v[174:177], v[182:185], v[114:117]
	v_mfma_f32_16x16x32_bf16 v[106:109], v[166:169], v[210:213], v[106:109]
	v_mfma_f32_16x16x32_bf16 v[98:101], v[174:177], v[210:213], v[98:101]
	v_mfma_f32_16x16x32_bf16 v[90:93], v[166:169], v[218:221], v[90:93]
	v_mfma_f32_16x16x32_bf16 v[82:85], v[174:177], v[218:221], v[82:85]
	v_mfma_f32_16x16x32_bf16 v[74:77], v[166:169], v[226:229], v[74:77]
	v_mfma_f32_16x16x32_bf16 v[66:69], v[174:177], v[226:229], v[66:69]
	s_barrier
	s_add_i32 s50, 0, 0x14000
	v_add_u32_e32 v140, s50, v143
	s_add_i32 s48, s48, s29
	ds_read_b128 v[230:233], v140
	ds_read_b128 v[234:237], v140 offset:1024
	ds_read_b128 v[238:241], v140 offset:2048
	ds_read_b128 v[242:245], v140 offset:3072
	v_lshl_add_u64 v[140:141], s[22:23], 0, v[0:1]
	s_mov_b32 m0, s48
	v_lshl_add_u64 v[186:187], s[22:23], 0, v[130:131]
	global_load_lds_dwordx4 v[140:141], off
	s_add_i32 m0, s48, 0x2000
	s_nop 0
	global_load_lds_dwordx4 v[186:187], off
	s_barrier
	s_waitcnt lgkmcnt(0)
	v_mfma_f32_16x16x32_bf16 v[126:129], v[230:233], v[178:181], v[126:129]
	v_mfma_f32_16x16x32_bf16 v[118:121], v[238:241], v[178:181], v[118:121]
	v_mfma_f32_16x16x32_bf16 v[110:113], v[230:233], v[206:209], v[110:113]
	v_mfma_f32_16x16x32_bf16 v[102:105], v[238:241], v[206:209], v[102:105]
	v_mfma_f32_16x16x32_bf16 v[94:97], v[230:233], v[214:217], v[94:97]
	v_mfma_f32_16x16x32_bf16 v[86:89], v[238:241], v[214:217], v[86:89]
	v_mfma_f32_16x16x32_bf16 v[78:81], v[230:233], v[222:225], v[78:81]
	v_mfma_f32_16x16x32_bf16 v[70:73], v[238:241], v[222:225], v[70:73]
	v_mfma_f32_16x16x32_bf16 v[126:129], v[234:237], v[182:185], v[126:129]
	v_mfma_f32_16x16x32_bf16 v[118:121], v[242:245], v[182:185], v[118:121]
	v_mfma_f32_16x16x32_bf16 v[110:113], v[234:237], v[210:213], v[110:113]
	v_mfma_f32_16x16x32_bf16 v[102:105], v[242:245], v[210:213], v[102:105]
	v_mfma_f32_16x16x32_bf16 v[94:97], v[234:237], v[218:221], v[94:97]
	v_mfma_f32_16x16x32_bf16 v[86:89], v[242:245], v[218:221], v[86:89]
	v_mfma_f32_16x16x32_bf16 v[78:81], v[234:237], v[226:229], v[78:81]
	v_mfma_f32_16x16x32_bf16 v[70:73], v[242:245], v[226:229], v[70:73]
	s_barrier
	s_mov_b32 m0, s3
	v_lshl_add_u64 v[246:247], s[24:25], 0, v[134:135]
	ds_read_b128 v[178:181], v145 offset:16384
	ds_read_b128 v[182:185], v145 offset:17408
	ds_read_b128 v[206:209], v145 offset:18432
	ds_read_b128 v[210:213], v145 offset:19456
	ds_read_b128 v[214:217], v145 offset:20480
	ds_read_b128 v[218:221], v145 offset:21504
	ds_read_b128 v[222:225], v145 offset:22528
	ds_read_b128 v[226:229], v145 offset:23552
	global_load_lds_dwordx4 v[246:247], off
	s_mov_b32 m0, s31
	v_lshl_add_u64 v[248:249], s[24:25], 0, v[132:133]
	global_load_lds_dwordx4 v[248:249], off
	s_barrier
	s_waitcnt lgkmcnt(0)
	v_mfma_f32_16x16x32_bf16 v[58:61], v[162:165], v[178:181], v[58:61]
	v_mfma_f32_16x16x32_bf16 v[50:53], v[170:173], v[178:181], v[50:53]
	v_mfma_f32_16x16x32_bf16 v[42:45], v[162:165], v[206:209], v[42:45]
	v_mfma_f32_16x16x32_bf16 v[34:37], v[170:173], v[206:209], v[34:37]
	v_mfma_f32_16x16x32_bf16 v[26:29], v[162:165], v[214:217], v[26:29]
	v_mfma_f32_16x16x32_bf16 v[18:21], v[170:173], v[214:217], v[18:21]
	v_mfma_f32_16x16x32_bf16 v[10:13], v[162:165], v[222:225], v[10:13]
	v_mfma_f32_16x16x32_bf16 v[6:9], v[170:173], v[222:225], v[6:9]
	v_mfma_f32_16x16x32_bf16 v[58:61], v[166:169], v[182:185], v[58:61]
	v_mfma_f32_16x16x32_bf16 v[50:53], v[174:177], v[182:185], v[50:53]
	v_mfma_f32_16x16x32_bf16 v[42:45], v[166:169], v[210:213], v[42:45]
	v_mfma_f32_16x16x32_bf16 v[34:37], v[174:177], v[210:213], v[34:37]
	v_mfma_f32_16x16x32_bf16 v[26:29], v[166:169], v[218:221], v[26:29]
	v_mfma_f32_16x16x32_bf16 v[18:21], v[174:177], v[218:221], v[18:21]
	v_mfma_f32_16x16x32_bf16 v[10:13], v[166:169], v[226:229], v[10:13]
	v_mfma_f32_16x16x32_bf16 v[6:9], v[174:177], v[226:229], v[6:9]
	s_barrier
	s_add_u32 s48, s22, 0x40000
	s_addc_u32 s49, s23, 0
	s_add_i32 s50, s50, s29
	s_mov_b32 m0, s50
	v_lshl_add_u64 v[162:163], s[48:49], 0, v[0:1]
	global_load_lds_dwordx4 v[162:163], off
	s_add_i32 m0, s50, 0x2000
	v_lshl_add_u64 v[162:163], s[48:49], 0, v[130:131]
	global_load_lds_dwordx4 v[162:163], off
	s_waitcnt vmcnt(6)
	s_barrier
	v_mfma_f32_16x16x32_bf16 v[62:65], v[230:233], v[178:181], v[62:65]
	v_mfma_f32_16x16x32_bf16 v[54:57], v[238:241], v[178:181], v[54:57]
	v_mfma_f32_16x16x32_bf16 v[46:49], v[230:233], v[206:209], v[46:49]
	v_mfma_f32_16x16x32_bf16 v[38:41], v[238:241], v[206:209], v[38:41]
	v_mfma_f32_16x16x32_bf16 v[30:33], v[230:233], v[214:217], v[30:33]
	v_mfma_f32_16x16x32_bf16 v[22:25], v[238:241], v[214:217], v[22:25]
	v_mfma_f32_16x16x32_bf16 v[14:17], v[230:233], v[222:225], v[14:17]
	v_mfma_f32_16x16x32_bf16 v[2:5], v[238:241], v[222:225], v[2:5]
	v_mfma_f32_16x16x32_bf16 v[62:65], v[234:237], v[182:185], v[62:65]
	v_mfma_f32_16x16x32_bf16 v[54:57], v[242:245], v[182:185], v[54:57]
	v_mfma_f32_16x16x32_bf16 v[46:49], v[234:237], v[210:213], v[46:49]
	v_mfma_f32_16x16x32_bf16 v[38:41], v[242:245], v[210:213], v[38:41]
	v_mfma_f32_16x16x32_bf16 v[30:33], v[234:237], v[218:221], v[30:33]
	v_mfma_f32_16x16x32_bf16 v[22:25], v[242:245], v[218:221], v[22:25]
	v_mfma_f32_16x16x32_bf16 v[14:17], v[234:237], v[226:229], v[14:17]
	v_mfma_f32_16x16x32_bf16 v[2:5], v[242:245], v[226:229], v[2:5]
	s_barrier
	s_add_i32 s48, 0, 0x18000
	v_add_u32_e32 v174, s48, v143
	ds_read_b128 v[162:165], v174
	ds_read_b128 v[166:169], v174 offset:1024
	ds_read_b128 v[170:173], v174 offset:2048
	ds_read_b128 v[174:177], v174 offset:3072
	s_add_u32 s24, s24, 0x40000
	s_addc_u32 s25, s25, 0
	s_mov_b32 m0, s34
	v_lshl_add_u64 v[230:231], s[24:25], 0, v[134:135]
	ds_read_b128 v[178:181], v145 offset:32768
	ds_read_b128 v[182:185], v145 offset:33792
	ds_read_b128 v[206:209], v145 offset:34816
	ds_read_b128 v[210:213], v145 offset:35840
	ds_read_b128 v[214:217], v145 offset:36864
	ds_read_b128 v[218:221], v145 offset:37888
	ds_read_b128 v[222:225], v145 offset:38912
	ds_read_b128 v[226:229], v145 offset:39936
	global_load_lds_dwordx4 v[230:231], off
	s_mov_b32 m0, s35
	v_lshl_add_u64 v[230:231], s[24:25], 0, v[132:133]
	global_load_lds_dwordx4 v[230:231], off
	s_waitcnt lgkmcnt(8)
	s_barrier
	s_waitcnt lgkmcnt(0)
	v_mfma_f32_16x16x32_bf16 v[122:125], v[162:165], v[178:181], v[122:125]
	v_mfma_f32_16x16x32_bf16 v[114:117], v[170:173], v[178:181], v[114:117]
	v_mfma_f32_16x16x32_bf16 v[106:109], v[162:165], v[206:209], v[106:109]
	v_mfma_f32_16x16x32_bf16 v[98:101], v[170:173], v[206:209], v[98:101]
	v_mfma_f32_16x16x32_bf16 v[90:93], v[162:165], v[214:217], v[90:93]
	v_mfma_f32_16x16x32_bf16 v[82:85], v[170:173], v[214:217], v[82:85]
	v_mfma_f32_16x16x32_bf16 v[74:77], v[162:165], v[222:225], v[74:77]
	v_mfma_f32_16x16x32_bf16 v[66:69], v[170:173], v[222:225], v[66:69]
	v_mfma_f32_16x16x32_bf16 v[122:125], v[166:169], v[182:185], v[122:125]
	v_mfma_f32_16x16x32_bf16 v[114:117], v[174:177], v[182:185], v[114:117]
	v_mfma_f32_16x16x32_bf16 v[106:109], v[166:169], v[210:213], v[106:109]
	v_mfma_f32_16x16x32_bf16 v[98:101], v[174:177], v[210:213], v[98:101]
	v_mfma_f32_16x16x32_bf16 v[90:93], v[166:169], v[218:221], v[90:93]
	v_mfma_f32_16x16x32_bf16 v[82:85], v[174:177], v[218:221], v[82:85]
	v_mfma_f32_16x16x32_bf16 v[74:77], v[166:169], v[226:229], v[74:77]
	v_mfma_f32_16x16x32_bf16 v[66:69], v[174:177], v[226:229], v[66:69]
	s_barrier
	s_add_i32 s24, 0, 0x1c000
	s_add_i32 s25, s48, s29
	v_add_u32_e32 v205, s24, v143
	v_lshl_add_u64 v[140:141], v[140:141], 0, s[94:95]
	s_mov_b32 m0, s25
	ds_read_b128 v[230:233], v205
	ds_read_b128 v[234:237], v205 offset:1024
	ds_read_b128 v[238:241], v205 offset:2048
	ds_read_b128 v[242:245], v205 offset:3072
	global_load_lds_dwordx4 v[140:141], off
	s_add_i32 m0, s25, 0x2000
	v_lshl_add_u64 v[140:141], v[186:187], 0, s[94:95]
	global_load_lds_dwordx4 v[140:141], off
	s_barrier
	s_waitcnt lgkmcnt(0)
	v_mfma_f32_16x16x32_bf16 v[126:129], v[230:233], v[178:181], v[126:129]
	v_mfma_f32_16x16x32_bf16 v[118:121], v[238:241], v[178:181], v[118:121]
	v_mfma_f32_16x16x32_bf16 v[110:113], v[230:233], v[206:209], v[110:113]
	v_mfma_f32_16x16x32_bf16 v[102:105], v[238:241], v[206:209], v[102:105]
	v_mfma_f32_16x16x32_bf16 v[94:97], v[230:233], v[214:217], v[94:97]
	v_mfma_f32_16x16x32_bf16 v[86:89], v[238:241], v[214:217], v[86:89]
	v_mfma_f32_16x16x32_bf16 v[78:81], v[230:233], v[222:225], v[78:81]
	v_mfma_f32_16x16x32_bf16 v[70:73], v[238:241], v[222:225], v[70:73]
	v_mfma_f32_16x16x32_bf16 v[126:129], v[234:237], v[182:185], v[126:129]
	v_mfma_f32_16x16x32_bf16 v[118:121], v[242:245], v[182:185], v[118:121]
	v_mfma_f32_16x16x32_bf16 v[110:113], v[234:237], v[210:213], v[110:113]
	v_mfma_f32_16x16x32_bf16 v[102:105], v[242:245], v[210:213], v[102:105]
	v_mfma_f32_16x16x32_bf16 v[94:97], v[234:237], v[218:221], v[94:97]
	v_mfma_f32_16x16x32_bf16 v[86:89], v[242:245], v[218:221], v[86:89]
	v_mfma_f32_16x16x32_bf16 v[78:81], v[234:237], v[226:229], v[78:81]
	v_mfma_f32_16x16x32_bf16 v[70:73], v[242:245], v[226:229], v[70:73]
	s_barrier
	s_mov_b32 m0, s37
	v_lshl_add_u64 v[140:141], v[246:247], 0, s[94:95]
	ds_read_b128 v[178:181], v145 offset:49152
	ds_read_b128 v[182:185], v145 offset:50176
	ds_read_b128 v[206:209], v145 offset:51200
	ds_read_b128 v[210:213], v145 offset:52224
	ds_read_b128 v[214:217], v145 offset:53248
	ds_read_b128 v[218:221], v145 offset:54272
	ds_read_b128 v[222:225], v145 offset:55296
	ds_read_b128 v[226:229], v145 offset:56320
	global_load_lds_dwordx4 v[140:141], off
	s_mov_b32 m0, s40
	v_lshl_add_u64 v[140:141], v[248:249], 0, s[94:95]
	global_load_lds_dwordx4 v[140:141], off
	s_barrier
	s_waitcnt lgkmcnt(0)
	v_mfma_f32_16x16x32_bf16 v[58:61], v[162:165], v[178:181], v[58:61]
	v_mfma_f32_16x16x32_bf16 v[50:53], v[170:173], v[178:181], v[50:53]
	v_mfma_f32_16x16x32_bf16 v[42:45], v[162:165], v[206:209], v[42:45]
	v_mfma_f32_16x16x32_bf16 v[34:37], v[170:173], v[206:209], v[34:37]
	v_mfma_f32_16x16x32_bf16 v[26:29], v[162:165], v[214:217], v[26:29]
	v_mfma_f32_16x16x32_bf16 v[18:21], v[170:173], v[214:217], v[18:21]
	v_mfma_f32_16x16x32_bf16 v[10:13], v[162:165], v[222:225], v[10:13]
	v_mfma_f32_16x16x32_bf16 v[6:9], v[170:173], v[222:225], v[6:9]
	v_mfma_f32_16x16x32_bf16 v[58:61], v[166:169], v[182:185], v[58:61]
	v_mfma_f32_16x16x32_bf16 v[50:53], v[174:177], v[182:185], v[50:53]
	v_mfma_f32_16x16x32_bf16 v[42:45], v[166:169], v[210:213], v[42:45]
	v_mfma_f32_16x16x32_bf16 v[34:37], v[174:177], v[210:213], v[34:37]
	v_mfma_f32_16x16x32_bf16 v[26:29], v[166:169], v[218:221], v[26:29]
	v_mfma_f32_16x16x32_bf16 v[18:21], v[174:177], v[218:221], v[18:21]
	v_mfma_f32_16x16x32_bf16 v[10:13], v[166:169], v[226:229], v[10:13]
	v_mfma_f32_16x16x32_bf16 v[6:9], v[174:177], v[226:229], v[6:9]
	s_barrier
	s_add_u32 s22, s22, 0x40080
	s_addc_u32 s23, s23, 0
	s_add_i32 s24, s24, s29
	s_mov_b32 m0, s24
	v_lshl_add_u64 v[140:141], s[22:23], 0, v[0:1]
	global_load_lds_dwordx4 v[140:141], off
	s_add_i32 m0, s24, 0x2000
	v_lshl_add_u64 v[140:141], s[22:23], 0, v[130:131]
	global_load_lds_dwordx4 v[140:141], off
	s_waitcnt vmcnt(6)
	s_barrier
	v_mfma_f32_16x16x32_bf16 v[62:65], v[230:233], v[178:181], v[62:65]
	v_mfma_f32_16x16x32_bf16 v[54:57], v[238:241], v[178:181], v[54:57]
	v_mfma_f32_16x16x32_bf16 v[46:49], v[230:233], v[206:209], v[46:49]
	v_mfma_f32_16x16x32_bf16 v[38:41], v[238:241], v[206:209], v[38:41]
	v_mfma_f32_16x16x32_bf16 v[30:33], v[230:233], v[214:217], v[30:33]
	v_mfma_f32_16x16x32_bf16 v[22:25], v[238:241], v[214:217], v[22:25]
	v_mfma_f32_16x16x32_bf16 v[14:17], v[230:233], v[222:225], v[14:17]
	v_mfma_f32_16x16x32_bf16 v[2:5], v[238:241], v[222:225], v[2:5]
	v_mfma_f32_16x16x32_bf16 v[62:65], v[234:237], v[182:185], v[62:65]
	v_mfma_f32_16x16x32_bf16 v[54:57], v[242:245], v[182:185], v[54:57]
	v_mfma_f32_16x16x32_bf16 v[46:49], v[234:237], v[210:213], v[46:49]
	v_mfma_f32_16x16x32_bf16 v[38:41], v[242:245], v[210:213], v[38:41]
	v_mfma_f32_16x16x32_bf16 v[30:33], v[234:237], v[218:221], v[30:33]
	v_mfma_f32_16x16x32_bf16 v[22:25], v[242:245], v[218:221], v[22:25]
	v_mfma_f32_16x16x32_bf16 v[14:17], v[234:237], v[226:229], v[14:17]
	v_mfma_f32_16x16x32_bf16 v[2:5], v[242:245], v[226:229], v[2:5]
	s_barrier
	s_add_i32 s47, s47, 2
	s_add_u32 s20, s20, 0x100
	s_addc_u32 s21, s21, 0
	s_add_u32 s45, s45, 0x100
	s_addc_u32 s46, s46, 0
	s_cmp_gt_u32 s47, 13
	s_cbranch_scc0 .LBB0_586
	v_pk_mul_f32 v[164:165], v[122:123], s[4:5] op_sel_hi:[1,0]
	v_pk_mul_f32 v[122:123], v[122:123], v[126:127]
	v_pk_mul_f32 v[126:127], v[114:115], s[4:5] op_sel_hi:[1,0]
	v_pk_mul_f32 v[114:115], v[114:115], v[118:119]
	v_exp_f32_e32 v126, v126
	v_exp_f32_e32 v127, v127
	v_pk_mul_f32 v[128:129], v[124:125], v[128:129]
	v_pk_mul_f32 v[124:125], v[124:125], s[4:5] op_sel_hi:[1,0]
	v_exp_f32_e32 v164, v164
	v_pk_add_f32 v[126:127], v[126:127], 1.0 op_sel_hi:[1,0]
	v_exp_f32_e32 v165, v165
	v_rcp_f32_e32 v126, v126
	v_rcp_f32_e32 v127, v127
	v_exp_f32_e32 v124, v124
	v_exp_f32_e32 v125, v125
	v_pk_add_f32 v[164:165], v[164:165], 1.0 op_sel_hi:[1,0]
	v_pk_mul_f32 v[118:119], v[126:127], v[114:115]
	v_pk_mul_f32 v[114:115], v[116:117], s[4:5] op_sel_hi:[1,0]
	v_pk_add_f32 v[124:125], v[124:125], 1.0 op_sel_hi:[1,0]
	v_exp_f32_e32 v114, v114
	v_exp_f32_e32 v115, v115
	v_rcp_f32_e32 v164, v164
	v_rcp_f32_e32 v165, v165
	v_rcp_f32_e32 v124, v124
	v_pk_add_f32 v[114:115], v[114:115], 1.0 op_sel_hi:[1,0]
	v_rcp_f32_e32 v125, v125
	v_rcp_f32_e32 v114, v114
	v_rcp_f32_e32 v115, v115
	v_lshl_or_b32 v140, s42, 7, v144
	v_ashrrev_i32_e32 v141, 31, v140
	v_lshl_add_u32 v162, s2, 8, v142
	v_lshl_add_u64 v[140:141], v[140:141], 1, s[14:15]
	v_pk_mul_f32 v[120:121], v[116:117], v[120:121]
	v_pk_mul_f32 v[122:123], v[164:165], v[122:123]
	v_pk_mul_f32 v[124:125], v[124:125], v[128:129]
	v_pk_mul_f32 v[120:121], v[114:115], v[120:121]
	v_mad_i64_i32 v[126:127], s[20:21], v162, s91, v[140:141]
	v_cvt_pk_bf16_f32 v114, v122, v123
	v_cvt_pk_bf16_f32 v115, v124, v125
	v_cvt_pk_bf16_f32 v116, v118, v119
	v_cvt_pk_bf16_f32 v117, v120, v121
	global_store_dwordx4 v[126:127], v[114:117], off
	v_pk_mul_f32 v[112:113], v[108:109], v[112:113]
	v_pk_mul_f32 v[108:109], v[108:109], s[4:5] op_sel_hi:[1,0]
	v_pk_mul_f32 v[114:115], v[106:107], s[4:5] op_sel_hi:[1,0]
	v_pk_mul_f32 v[106:107], v[106:107], v[110:111]
	v_pk_mul_f32 v[110:111], v[98:99], s[4:5] op_sel_hi:[1,0]
	v_pk_mul_f32 v[98:99], v[98:99], v[102:103]
	v_exp_f32_e32 v110, v110
	v_exp_f32_e32 v111, v111
	v_exp_f32_e32 v114, v114
	v_exp_f32_e32 v115, v115
	v_exp_f32_e32 v108, v108
	v_pk_add_f32 v[110:111], v[110:111], 1.0 op_sel_hi:[1,0]
	v_exp_f32_e32 v109, v109
	v_rcp_f32_e32 v110, v110
	v_rcp_f32_e32 v111, v111
	v_pk_add_f32 v[114:115], v[114:115], 1.0 op_sel_hi:[1,0]
	v_pk_add_f32 v[108:109], v[108:109], 1.0 op_sel_hi:[1,0]
	v_rcp_f32_e32 v114, v114
	v_pk_mul_f32 v[102:103], v[110:111], v[98:99]
	v_pk_mul_f32 v[98:99], v[100:101], s[4:5] op_sel_hi:[1,0]
	v_rcp_f32_e32 v115, v115
	v_exp_f32_e32 v98, v98
	v_exp_f32_e32 v99, v99
	v_rcp_f32_e32 v108, v108
	v_rcp_f32_e32 v109, v109
	v_or_b32_e32 v116, 16, v162
	v_pk_add_f32 v[98:99], v[98:99], 1.0 op_sel_hi:[1,0]
	v_pk_mul_f32 v[104:105], v[100:101], v[104:105]
	v_rcp_f32_e32 v98, v98
	v_rcp_f32_e32 v99, v99
	v_pk_mul_f32 v[106:107], v[114:115], v[106:107]
	v_pk_mul_f32 v[108:109], v[108:109], v[112:113]
	v_mad_i64_i32 v[110:111], s[20:21], v116, s91, v[140:141]
	v_pk_mul_f32 v[104:105], v[98:99], v[104:105]
	v_cvt_pk_bf16_f32 v98, v106, v107
	v_cvt_pk_bf16_f32 v99, v108, v109
	v_cvt_pk_bf16_f32 v100, v102, v103
	v_pk_mul_f32 v[96:97], v[92:93], v[96:97]
	v_cvt_pk_bf16_f32 v101, v104, v105
	global_store_dwordx4 v[110:111], v[98:101], off
	v_pk_mul_f32 v[92:93], v[92:93], s[4:5] op_sel_hi:[1,0]
	v_pk_mul_f32 v[88:89], v[84:85], v[88:89]
	v_pk_mul_f32 v[98:99], v[90:91], s[4:5] op_sel_hi:[1,0]
	v_pk_mul_f32 v[90:91], v[90:91], v[94:95]
	v_pk_mul_f32 v[94:95], v[82:83], s[4:5] op_sel_hi:[1,0]
	v_pk_mul_f32 v[82:83], v[82:83], v[86:87]
	v_exp_f32_e32 v94, v94
	v_exp_f32_e32 v95, v95
	v_exp_f32_e32 v98, v98
	v_exp_f32_e32 v99, v99
	v_exp_f32_e32 v92, v92
	v_pk_add_f32 v[94:95], v[94:95], 1.0 op_sel_hi:[1,0]
	v_exp_f32_e32 v93, v93
	v_rcp_f32_e32 v94, v94
	v_rcp_f32_e32 v95, v95
	v_pk_add_f32 v[98:99], v[98:99], 1.0 op_sel_hi:[1,0]
	v_pk_add_f32 v[92:93], v[92:93], 1.0 op_sel_hi:[1,0]
	v_rcp_f32_e32 v98, v98
	v_pk_mul_f32 v[86:87], v[94:95], v[82:83]
	v_pk_mul_f32 v[82:83], v[84:85], s[4:5] op_sel_hi:[1,0]
	v_rcp_f32_e32 v99, v99
	v_exp_f32_e32 v82, v82
	v_exp_f32_e32 v83, v83
	v_rcp_f32_e32 v92, v92
	v_rcp_f32_e32 v93, v93
	v_or_b32_e32 v100, 32, v162
	v_pk_add_f32 v[82:83], v[82:83], 1.0 op_sel_hi:[1,0]
	v_pk_mul_f32 v[90:91], v[98:99], v[90:91]
	v_rcp_f32_e32 v82, v82
	v_rcp_f32_e32 v83, v83
	v_pk_mul_f32 v[92:93], v[92:93], v[96:97]
	v_mad_i64_i32 v[94:95], s[20:21], v100, s91, v[140:141]
	v_pk_mul_f32 v[88:89], v[82:83], v[88:89]
	v_cvt_pk_bf16_f32 v82, v90, v91
	v_cvt_pk_bf16_f32 v83, v92, v93
	v_cvt_pk_bf16_f32 v84, v86, v87
	v_pk_mul_f32 v[80:81], v[76:77], v[80:81]
	v_cvt_pk_bf16_f32 v85, v88, v89
	global_store_dwordx4 v[94:95], v[82:85], off
	v_pk_mul_f32 v[76:77], v[76:77], s[4:5] op_sel_hi:[1,0]
	v_pk_mul_f32 v[72:73], v[68:69], v[72:73]
	v_pk_mul_f32 v[82:83], v[74:75], s[4:5] op_sel_hi:[1,0]
	v_pk_mul_f32 v[74:75], v[74:75], v[78:79]
	v_pk_mul_f32 v[78:79], v[66:67], s[4:5] op_sel_hi:[1,0]
	v_pk_mul_f32 v[66:67], v[66:67], v[70:71]
	v_exp_f32_e32 v78, v78
	v_exp_f32_e32 v79, v79
	v_exp_f32_e32 v82, v82
	v_exp_f32_e32 v83, v83
	v_exp_f32_e32 v76, v76
	v_pk_add_f32 v[78:79], v[78:79], 1.0 op_sel_hi:[1,0]
	v_exp_f32_e32 v77, v77
	v_rcp_f32_e32 v78, v78
	v_rcp_f32_e32 v79, v79
	v_pk_add_f32 v[82:83], v[82:83], 1.0 op_sel_hi:[1,0]
	v_pk_add_f32 v[76:77], v[76:77], 1.0 op_sel_hi:[1,0]
	v_rcp_f32_e32 v82, v82
	v_pk_mul_f32 v[70:71], v[78:79], v[66:67]
	v_pk_mul_f32 v[66:67], v[68:69], s[4:5] op_sel_hi:[1,0]
	v_rcp_f32_e32 v83, v83
	v_exp_f32_e32 v66, v66
	v_exp_f32_e32 v67, v67
	v_rcp_f32_e32 v76, v76
	v_rcp_f32_e32 v77, v77
	v_or_b32_e32 v84, 48, v162
	v_pk_add_f32 v[66:67], v[66:67], 1.0 op_sel_hi:[1,0]
	v_pk_mul_f32 v[74:75], v[82:83], v[74:75]
	v_rcp_f32_e32 v66, v66
	v_rcp_f32_e32 v67, v67
	v_pk_mul_f32 v[76:77], v[76:77], v[80:81]
	v_mad_i64_i32 v[78:79], s[20:21], v84, s91, v[140:141]
	v_pk_mul_f32 v[72:73], v[66:67], v[72:73]
	v_cvt_pk_bf16_f32 v66, v74, v75
	v_cvt_pk_bf16_f32 v67, v76, v77
	v_cvt_pk_bf16_f32 v68, v70, v71
	v_pk_mul_f32 v[64:65], v[60:61], v[64:65]
	v_cvt_pk_bf16_f32 v69, v72, v73
	global_store_dwordx4 v[78:79], v[66:69], off
	v_pk_mul_f32 v[60:61], v[60:61], s[4:5] op_sel_hi:[1,0]
	v_pk_mul_f32 v[56:57], v[52:53], v[56:57]
	v_pk_mul_f32 v[66:67], v[58:59], s[4:5] op_sel_hi:[1,0]
	v_pk_mul_f32 v[58:59], v[58:59], v[62:63]
	v_pk_mul_f32 v[62:63], v[50:51], s[4:5] op_sel_hi:[1,0]
	v_pk_mul_f32 v[50:51], v[50:51], v[54:55]
	v_exp_f32_e32 v62, v62
	v_exp_f32_e32 v63, v63
	v_exp_f32_e32 v66, v66
	v_exp_f32_e32 v67, v67
	v_exp_f32_e32 v60, v60
	v_pk_add_f32 v[62:63], v[62:63], 1.0 op_sel_hi:[1,0]
	v_exp_f32_e32 v61, v61
	v_rcp_f32_e32 v62, v62
	v_rcp_f32_e32 v63, v63
	v_pk_add_f32 v[66:67], v[66:67], 1.0 op_sel_hi:[1,0]
	v_pk_add_f32 v[60:61], v[60:61], 1.0 op_sel_hi:[1,0]
	v_rcp_f32_e32 v66, v66
	v_pk_mul_f32 v[54:55], v[62:63], v[50:51]
	v_pk_mul_f32 v[50:51], v[52:53], s[4:5] op_sel_hi:[1,0]
	v_rcp_f32_e32 v67, v67
	v_exp_f32_e32 v50, v50
	v_exp_f32_e32 v51, v51
	v_rcp_f32_e32 v60, v60
	v_rcp_f32_e32 v61, v61
	v_add_u32_e32 v68, 0x80, v162
	v_pk_add_f32 v[50:51], v[50:51], 1.0 op_sel_hi:[1,0]
	v_pk_mul_f32 v[58:59], v[66:67], v[58:59]
	v_rcp_f32_e32 v50, v50
	v_rcp_f32_e32 v51, v51
	v_pk_mul_f32 v[60:61], v[60:61], v[64:65]
	v_mad_i64_i32 v[62:63], s[20:21], v68, s91, v[140:141]
	v_pk_mul_f32 v[56:57], v[50:51], v[56:57]
	v_cvt_pk_bf16_f32 v50, v58, v59
	v_cvt_pk_bf16_f32 v51, v60, v61
	v_cvt_pk_bf16_f32 v52, v54, v55
	v_pk_mul_f32 v[48:49], v[44:45], v[48:49]
	v_cvt_pk_bf16_f32 v53, v56, v57
	global_store_dwordx4 v[62:63], v[50:53], off
	v_pk_mul_f32 v[44:45], v[44:45], s[4:5] op_sel_hi:[1,0]
	v_pk_mul_f32 v[40:41], v[36:37], v[40:41]
	v_pk_mul_f32 v[50:51], v[42:43], s[4:5] op_sel_hi:[1,0]
	v_pk_mul_f32 v[42:43], v[42:43], v[46:47]
	v_pk_mul_f32 v[46:47], v[34:35], s[4:5] op_sel_hi:[1,0]
	v_pk_mul_f32 v[34:35], v[34:35], v[38:39]
	v_exp_f32_e32 v46, v46
	v_exp_f32_e32 v47, v47
	v_exp_f32_e32 v50, v50
	v_exp_f32_e32 v51, v51
	v_exp_f32_e32 v44, v44
	v_pk_add_f32 v[46:47], v[46:47], 1.0 op_sel_hi:[1,0]
	v_exp_f32_e32 v45, v45
	v_rcp_f32_e32 v46, v46
	v_rcp_f32_e32 v47, v47
	v_pk_add_f32 v[50:51], v[50:51], 1.0 op_sel_hi:[1,0]
	v_pk_add_f32 v[44:45], v[44:45], 1.0 op_sel_hi:[1,0]
	v_rcp_f32_e32 v50, v50
	v_pk_mul_f32 v[38:39], v[46:47], v[34:35]
	v_pk_mul_f32 v[34:35], v[36:37], s[4:5] op_sel_hi:[1,0]
	v_rcp_f32_e32 v51, v51
	v_exp_f32_e32 v34, v34
	v_exp_f32_e32 v35, v35
	v_rcp_f32_e32 v44, v44
	v_rcp_f32_e32 v45, v45
	v_add_u32_e32 v52, 0x90, v162
	v_pk_add_f32 v[34:35], v[34:35], 1.0 op_sel_hi:[1,0]
	v_pk_mul_f32 v[42:43], v[50:51], v[42:43]
	v_rcp_f32_e32 v34, v34
	v_rcp_f32_e32 v35, v35
	v_pk_mul_f32 v[44:45], v[44:45], v[48:49]
	v_mad_i64_i32 v[46:47], s[20:21], v52, s91, v[140:141]
	v_pk_mul_f32 v[40:41], v[34:35], v[40:41]
	v_cvt_pk_bf16_f32 v34, v42, v43
	v_cvt_pk_bf16_f32 v35, v44, v45
	v_cvt_pk_bf16_f32 v36, v38, v39
	v_pk_mul_f32 v[32:33], v[28:29], v[32:33]
	v_cvt_pk_bf16_f32 v37, v40, v41
	global_store_dwordx4 v[46:47], v[34:37], off
	v_pk_mul_f32 v[28:29], v[28:29], s[4:5] op_sel_hi:[1,0]
	v_pk_mul_f32 v[24:25], v[20:21], v[24:25]
	v_pk_mul_f32 v[34:35], v[26:27], s[4:5] op_sel_hi:[1,0]
	v_pk_mul_f32 v[26:27], v[26:27], v[30:31]
	v_pk_mul_f32 v[30:31], v[18:19], s[4:5] op_sel_hi:[1,0]
	v_pk_mul_f32 v[18:19], v[18:19], v[22:23]
	v_exp_f32_e32 v30, v30
	v_exp_f32_e32 v31, v31
	v_exp_f32_e32 v34, v34
	v_exp_f32_e32 v35, v35
	v_exp_f32_e32 v28, v28
	v_pk_add_f32 v[30:31], v[30:31], 1.0 op_sel_hi:[1,0]
	v_exp_f32_e32 v29, v29
	v_rcp_f32_e32 v30, v30
	v_rcp_f32_e32 v31, v31
	v_pk_add_f32 v[34:35], v[34:35], 1.0 op_sel_hi:[1,0]
	v_pk_add_f32 v[28:29], v[28:29], 1.0 op_sel_hi:[1,0]
	v_rcp_f32_e32 v34, v34
	v_pk_mul_f32 v[22:23], v[30:31], v[18:19]
	v_pk_mul_f32 v[18:19], v[20:21], s[4:5] op_sel_hi:[1,0]
	v_rcp_f32_e32 v35, v35
	v_exp_f32_e32 v18, v18
	v_exp_f32_e32 v19, v19
	v_rcp_f32_e32 v28, v28
	v_rcp_f32_e32 v29, v29
	v_add_u32_e32 v36, 0xa0, v162
	v_pk_add_f32 v[18:19], v[18:19], 1.0 op_sel_hi:[1,0]
	v_pk_mul_f32 v[26:27], v[34:35], v[26:27]
	v_rcp_f32_e32 v18, v18
	v_rcp_f32_e32 v19, v19
	v_pk_mul_f32 v[28:29], v[28:29], v[32:33]
	v_mad_i64_i32 v[30:31], s[20:21], v36, s91, v[140:141]
	v_pk_mul_f32 v[24:25], v[18:19], v[24:25]
	v_cvt_pk_bf16_f32 v18, v26, v27
	v_cvt_pk_bf16_f32 v19, v28, v29
	v_cvt_pk_bf16_f32 v20, v22, v23
	v_pk_mul_f32 v[2:3], v[6:7], v[2:3]
	v_cvt_pk_bf16_f32 v21, v24, v25
	global_store_dwordx4 v[30:31], v[18:21], off
	v_pk_mul_f32 v[16:17], v[12:13], v[16:17]
	v_pk_mul_f32 v[12:13], v[12:13], s[4:5] op_sel_hi:[1,0]
	v_pk_mul_f32 v[18:19], v[10:11], s[4:5] op_sel_hi:[1,0]
	v_pk_mul_f32 v[10:11], v[10:11], v[14:15]
	v_pk_mul_f32 v[14:15], v[6:7], s[4:5] op_sel_hi:[1,0]
	v_exp_f32_e32 v18, v18
	v_exp_f32_e32 v14, v14
	v_exp_f32_e32 v15, v15
	v_exp_f32_e32 v19, v19
	v_exp_f32_e32 v12, v12
	v_exp_f32_e32 v13, v13
	v_pk_add_f32 v[14:15], v[14:15], 1.0 op_sel_hi:[1,0]
	v_pk_add_f32 v[18:19], v[18:19], 1.0 op_sel_hi:[1,0]
	v_rcp_f32_e32 v14, v14
	v_rcp_f32_e32 v15, v15
	v_pk_add_f32 v[12:13], v[12:13], 1.0 op_sel_hi:[1,0]
	v_rcp_f32_e32 v18, v18
	v_rcp_f32_e32 v19, v19
	v_pk_mul_f32 v[6:7], v[14:15], v[2:3]
	v_pk_mul_f32 v[2:3], v[8:9], s[4:5] op_sel_hi:[1,0]
	v_rcp_f32_e32 v12, v12
	v_exp_f32_e32 v2, v2
	v_exp_f32_e32 v3, v3
	v_rcp_f32_e32 v13, v13
	v_add_u32_e32 v20, 0xb0, v162
	v_mad_i64_i32 v[14:15], s[20:21], v20, s91, v[140:141]
	v_pk_add_f32 v[2:3], v[2:3], 1.0 op_sel_hi:[1,0]
	v_pk_mul_f32 v[4:5], v[8:9], v[4:5]
	v_rcp_f32_e32 v2, v2
	v_rcp_f32_e32 v3, v3
	s_and_b64 vcc, exec, s[38:39]
	s_mov_b32 s42, s0
	s_mov_b32 s2, s8
	s_mov_b64 s[22:23], s[18:19]
	s_mov_b64 s[20:21], s[16:17]
	v_pk_mul_f32 v[10:11], v[18:19], v[10:11]
	v_pk_mul_f32 v[12:13], v[12:13], v[16:17]
	v_pk_mul_f32 v[8:9], v[2:3], v[4:5]
	v_cvt_pk_bf16_f32 v2, v10, v11
	v_cvt_pk_bf16_f32 v3, v12, v13
	v_cvt_pk_bf16_f32 v4, v6, v7
	s_nop 0
	v_cvt_pk_bf16_f32 v5, v8, v9
	global_store_dwordx4 v[14:15], v[2:5], off
	s_cbranch_vccz .LBB0_579
	s_waitcnt vmcnt(0)
	s_cmpk_gt_u32 s26, 0xff
	s_cbranch_scc1 .LBB0_590
	s_barrier
